# attention: QK MFMAs of a step use the softmax reference the step started with (C operand updated, and the fresh scores re-expressed, only in the rare re-reference path at the end of the step) - no wai
# baseline (speedup 1.0000x reference)
; #define AT_GLOADK(k0) do { kreg = *(const u32x4*)(Kb + (size_t)((k0) + (tid >> 3)) * 64 + (tid & 7) * 8); \
;             if (MLA) preg = *(const u32x2*)(Pb + (size_t)((k0) + (tid >> 3)) * 32 + (tid & 7) * 4); } while (0)
; #define AT_GLOADV(k0) do { vreg = *(const u32x4*)(Vb + (size_t)((k0) + (tid >> 3)) * 64 + (tid & 7) * 8); } while (0)
; #define AT_WRITEK(buf) do { *(LAS u32x4*)(lds + (buf) * KBUF + (tid >> 3) * KSTR + (tid & 7) * 16) = kreg; \
;             if (MLA) *(LAS u32x2*)(lds + (buf) * KBUF + (tid >> 3) * KSTR + 128 + (tid & 7) * 8) = preg; } while (0)
; #define AT_WRITEV(buf) do { *(LAS u32x4*)(lds + 2 * KBUF + (buf) * VBUF + (tid >> 3) * VSTR + (tid & 7) * 16) = vreg; } while (0)
; #define AT_STEP(SC0, SC1, SN0, SN1, t, DOK, DOV) do { \
;             if (DOK) AT_GLOADK(((t) + 2) * 64); \
;             if (DOV) { AT_GLOADV(((t) + 1) * 64); AT_QK(SN0, SN1, ((t) + 1) & 1); } \
;             AT_SMPV(SC0, SC1, (t) & 1); \
;             if (DOK) AT_WRITEK((t) & 1); \
;             if (DOV) AT_WRITEV(((t) + 1) & 1); \
;             __syncthreads(); } while (0)
; template <bool MLA>
; DI void attn_phase(const int TID, const int BID, LAS unsigned char* lds, const Params& p, bool need_ctx) {
;     ...
;         const int ntile = nk >> 6;
;         AT_GLOADK(0); AT_GLOADV(0); AT_WRITEK(0); AT_WRITEV(0);
;         AT_GLOADK(64); AT_WRITEK(1);
;         __syncthreads();
;         AT_QK(sa0, sa1, 0);
;         __syncthreads();
;         int t = 0;
;         for (; t < ntile - 2; t += 2) {
;             AT_STEP(sa0, sa1, sb0, sb1, t, true, true);
;             AT_STEP(sb0, sb1, sa0, sa1, t + 1, true, true);
;         }
.Lamla_prio:
	ds_read_b128 v[136:139], v243 offset:0
	ds_read_b128 v[140:143], v243 offset:6656
	ds_read_b128 v[144:147], v243 offset:32
	ds_read_b128 v[148:151], v243 offset:6688
	s_waitcnt lgkmcnt(3)
	v_mfma_f32_32x32x16_bf16 v[32:47], v[136:139], v[112:115], 0
	ds_read_b128 v[136:139], v243 offset:64
	s_waitcnt lgkmcnt(3)
	v_mfma_f32_32x32x16_bf16 v[48:63], v[140:143], v[112:115], 0
	ds_read_b128 v[140:143], v243 offset:6720
	s_waitcnt lgkmcnt(3)
	v_mfma_f32_32x32x16_bf16 v[32:47], v[144:147], v[116:119], v[32:47]
	ds_read_b128 v[144:147], v243 offset:96
	s_waitcnt lgkmcnt(3)
	v_mfma_f32_32x32x16_bf16 v[48:63], v[148:151], v[116:119], v[48:63]
	ds_read_b128 v[148:151], v243 offset:6752
	s_waitcnt lgkmcnt(3)
	v_mfma_f32_32x32x16_bf16 v[32:47], v[136:139], v[120:123], v[32:47]
	ds_read_b128 v[136:139], v243 offset:128
	s_waitcnt lgkmcnt(3)
	v_mfma_f32_32x32x16_bf16 v[48:63], v[140:143], v[120:123], v[48:63]
	ds_read_b128 v[140:143], v243 offset:6784
	s_waitcnt lgkmcnt(3)
	v_mfma_f32_32x32x16_bf16 v[32:47], v[144:147], v[124:127], v[32:47]
	ds_read_b128 v[144:147], v243 offset:160
	s_waitcnt lgkmcnt(3)
	v_mfma_f32_32x32x16_bf16 v[48:63], v[148:151], v[124:127], v[48:63]
	ds_read_b128 v[148:151], v243 offset:6816
	s_waitcnt lgkmcnt(3)
	v_mfma_f32_32x32x16_bf16 v[32:47], v[136:139], v[128:131], v[32:47]
	s_waitcnt lgkmcnt(2)
	v_mfma_f32_32x32x16_bf16 v[48:63], v[140:143], v[128:131], v[48:63]
	s_waitcnt lgkmcnt(1)
	v_mfma_f32_32x32x16_bf16 v[32:47], v[144:147], v[132:135], v[32:47]
	s_waitcnt lgkmcnt(0)
	v_mfma_f32_32x32x16_bf16 v[48:63], v[148:151], v[132:135], v[48:63]
	s_waitcnt lgkmcnt(0)
	s_nop 7
	s_barrier
	ds_read_b128 v[136:139], v243 offset:13312
	ds_read_b128 v[140:143], v243 offset:19968
	ds_read_b128 v[144:147], v243 offset:13344
	ds_read_b128 v[148:151], v243 offset:20000
	s_waitcnt lgkmcnt(3)
	v_mfma_f32_32x32x16_bf16 v[64:79], v[136:139], v[112:115], v[218:233]
	v_max3_f32 v168, v32, v33, v34
	v_max3_f32 v170, v48, v49, v50
	v_max3_f32 v168, v168, v35, v36
	v_max3_f32 v170, v170, v51, v52
	v_max3_f32 v168, v168, v37, v38
	v_max3_f32 v170, v170, v53, v54
	v_max3_f32 v168, v168, v39, v40
	v_max3_f32 v170, v170, v55, v56
	v_max3_f32 v168, v168, v41, v42
	ds_read_b128 v[136:139], v243 offset:13376
	s_mov_b32 s55, s52
	s_mov_b32 s52, s53
	s_mov_b32 s53, s54
	s_mov_b32 s54, s55
	s_mov_b32 s9, 0
	s_waitcnt lgkmcnt(3)
	v_mfma_f32_32x32x16_bf16 v[80:95], v[140:143], v[112:115], v[218:233]
	v_max3_f32 v170, v170, v57, v58
	v_max3_f32 v168, v168, v43, v44
	v_max3_f32 v170, v170, v59, v60
	v_max3_f32 v168, v168, v45, v46
	v_max3_f32 v170, v170, v61, v62
	v_max3_f32 v168, v168, v170, v47
	v_max_f32_e32 v168, v168, v63
	v_mov_b32_e32 v170, v168
	s_nop 1
	v_permlane32_swap_b32_e32 v168, v170
	v_max_f32_e32 v168, v168, v170
	v_mov_b32_e32 v170, v168
	v_sub_f32_e32 v32, v32, v170
	v_sub_f32_e32 v33, v33, v170
	v_sub_f32_e32 v34, v34, v170
	v_sub_f32_e32 v35, v35, v170
	v_sub_f32_e32 v36, v36, v170
	v_sub_f32_e32 v37, v37, v170
	v_sub_f32_e32 v38, v38, v170
	v_sub_f32_e32 v39, v39, v170
	v_sub_f32_e32 v40, v40, v170
	v_sub_f32_e32 v41, v41, v170
	v_sub_f32_e32 v42, v42, v170
	v_sub_f32_e32 v43, v43, v170
	v_sub_f32_e32 v44, v44, v170
	v_sub_f32_e32 v45, v45, v170
	v_sub_f32_e32 v46, v46, v170
	v_sub_f32_e32 v47, v47, v170
	v_sub_f32_e32 v48, v48, v170
	v_sub_f32_e32 v49, v49, v170
	v_sub_f32_e32 v50, v50, v170
	v_sub_f32_e32 v51, v51, v170
	v_sub_f32_e32 v52, v52, v170
	v_sub_f32_e32 v53, v53, v170
	v_sub_f32_e32 v54, v54, v170
	v_sub_f32_e32 v55, v55, v170
	v_sub_f32_e32 v56, v56, v170
	v_sub_f32_e32 v57, v57, v170
	v_sub_f32_e32 v58, v58, v170
	v_sub_f32_e32 v59, v59, v170
	v_sub_f32_e32 v60, v60, v170
	v_sub_f32_e32 v61, v61, v170
	v_sub_f32_e32 v62, v62, v170
	v_sub_f32_e32 v63, v63, v170
	ds_read_b128 v[140:143], v243 offset:20032
	global_load_dwordx4 v[208:211], v167, s[2:3]
	global_load_dwordx2 v[216:217], v165, s[10:11]
	global_load_dwordx4 v[212:215], v167, s[4:5]
	s_add_u32 s2, s2, 0x2000
	s_addc_u32 s3, s3, 0
	s_add_u32 s10, s10, 0x1000
	s_addc_u32 s11, s11, 0
	s_add_u32 s4, s4, 0x2000
	s_addc_u32 s5, s5, 0
	v_add_u32_e32 v163, s53, v240
	v_add_u32_e32 v164, s54, v241
	s_waitcnt lgkmcnt(3)
	v_mfma_f32_32x32x16_bf16 v[64:79], v[144:147], v[116:119], v[64:79]
	v_exp_f32_e32 v32, v32
	v_exp_f32_e32 v48, v48
	v_exp_f32_e32 v33, v33
	v_exp_f32_e32 v49, v49
	ds_read_b128 v[144:147], v243 offset:13408
	s_waitcnt lgkmcnt(3)
	v_mfma_f32_32x32x16_bf16 v[80:95], v[148:151], v[116:119], v[80:95]
	v_exp_f32_e32 v34, v34
	v_exp_f32_e32 v50, v50
	v_cvt_pk_bf16_f32 v96, v32, v33
	v_cvt_pk_bf16_f32 v104, v48, v49
	v_exp_f32_e32 v35, v35
	ds_read_b128 v[148:151], v243 offset:20064
	s_waitcnt lgkmcnt(3)
	v_mfma_f32_32x32x16_bf16 v[64:79], v[136:139], v[120:123], v[64:79]
	v_exp_f32_e32 v51, v51
	v_exp_f32_e32 v36, v36
	v_exp_f32_e32 v52, v52
	v_cvt_pk_bf16_f32 v97, v34, v35
	ds_read_b128 v[136:139], v243 offset:13440
	s_waitcnt lgkmcnt(3)
	v_mfma_f32_32x32x16_bf16 v[80:95], v[140:143], v[120:123], v[80:95]
	v_cvt_pk_bf16_f32 v105, v50, v51
	v_exp_f32_e32 v37, v37
	v_exp_f32_e32 v53, v53
	v_exp_f32_e32 v38, v38
	v_exp_f32_e32 v54, v54
	ds_read_b128 v[140:143], v243 offset:20096
	s_waitcnt lgkmcnt(3)
	v_mfma_f32_32x32x16_bf16 v[64:79], v[144:147], v[124:127], v[64:79]
	v_cvt_pk_bf16_f32 v98, v36, v37
	v_cvt_pk_bf16_f32 v106, v52, v53
	v_exp_f32_e32 v39, v39
	v_exp_f32_e32 v55, v55
	v_exp_f32_e32 v40, v40
	ds_read_b128 v[144:147], v243 offset:13472
	ds_read_b64_tr_b16 v[176:177], v163 offset:0
	ds_read_b64_tr_b16 v[178:179], v163 offset:1536
	s_waitcnt vmcnt(5)
	ds_write_b128 v238, v[152:155]
	s_waitcnt vmcnt(4)
	ds_write_b64 v239, v[160:161]
	s_waitcnt vmcnt(3)
	ds_write_b128 v164, v[156:159]
	s_waitcnt lgkmcnt(8)
	v_mfma_f32_32x32x16_bf16 v[80:95], v[148:151], v[124:127], v[80:95]
	v_exp_f32_e32 v56, v56
	v_cvt_pk_bf16_f32 v99, v38, v39
	v_cvt_pk_bf16_f32 v107, v54, v55
	v_exp_f32_e32 v41, v41
	v_exp_f32_e32 v57, v57
	ds_read_b128 v[148:151], v243 offset:20128
	ds_read_b64_tr_b16 v[180:181], v163 offset:64
	ds_read_b64_tr_b16 v[182:183], v163 offset:1600
	s_waitcnt lgkmcnt(10)
	v_mfma_f32_32x32x16_bf16 v[64:79], v[136:139], v[128:131], v[64:79]
	v_exp_f32_e32 v42, v42
	v_exp_f32_e32 v58, v58
	v_cvt_pk_bf16_f32 v100, v40, v41
	v_cvt_pk_bf16_f32 v108, v56, v57
	v_exp_f32_e32 v43, v43
	ds_read_b64_tr_b16 v[184:185], v163 offset:6144
	ds_read_b64_tr_b16 v[186:187], v163 offset:7680
	s_waitcnt lgkmcnt(11)
	v_mfma_f32_32x32x16_bf16 v[80:95], v[140:143], v[128:131], v[80:95]
	v_exp_f32_e32 v59, v59
	v_exp_f32_e32 v44, v44
	v_exp_f32_e32 v60, v60
	v_cvt_pk_bf16_f32 v101, v42, v43
	v_cvt_pk_bf16_f32 v109, v58, v59
	ds_read_b64_tr_b16 v[188:189], v163 offset:6208
	ds_read_b64_tr_b16 v[190:191], v163 offset:7744
	s_waitcnt lgkmcnt(12)
	v_mfma_f32_32x32x16_bf16 v[64:79], v[144:147], v[132:135], v[64:79]
	v_exp_f32_e32 v45, v45
	v_exp_f32_e32 v61, v61
	v_exp_f32_e32 v46, v46
	v_exp_f32_e32 v62, v62
	s_waitcnt lgkmcnt(6)
	v_mfma_f32_32x32x16_bf16 v[80:95], v[148:151], v[132:135], v[80:95]
	v_cvt_pk_bf16_f32 v102, v44, v45
	v_cvt_pk_bf16_f32 v110, v60, v61
	v_exp_f32_e32 v47, v47
	v_exp_f32_e32 v63, v63
	v_cvt_pk_bf16_f32 v103, v46, v47
	v_cvt_pk_bf16_f32 v111, v62, v63
	s_nop 15
	v_sub_f32_e32 v218, v218, v170
	v_sub_f32_e32 v219, v219, v170
	v_sub_f32_e32 v220, v220, v170
	v_sub_f32_e32 v221, v221, v170
	v_sub_f32_e32 v222, v222, v170
	v_sub_f32_e32 v223, v223, v170
	v_sub_f32_e32 v224, v224, v170
	v_sub_f32_e32 v225, v225, v170
	v_sub_f32_e32 v226, v226, v170
	v_sub_f32_e32 v227, v227, v170
	v_sub_f32_e32 v228, v228, v170
	v_sub_f32_e32 v229, v229, v170
	v_sub_f32_e32 v230, v230, v170
	v_sub_f32_e32 v231, v231, v170
	v_sub_f32_e32 v232, v232, v170
	v_sub_f32_e32 v233, v233, v170
	v_sub_f32_e32 v64, v64, v170
	v_sub_f32_e32 v65, v65, v170
	v_sub_f32_e32 v66, v66, v170
	v_sub_f32_e32 v67, v67, v170
	v_sub_f32_e32 v68, v68, v170
	v_sub_f32_e32 v69, v69, v170
	v_sub_f32_e32 v70, v70, v170
	v_sub_f32_e32 v71, v71, v170
	v_sub_f32_e32 v72, v72, v170
	v_sub_f32_e32 v73, v73, v170
	v_sub_f32_e32 v74, v74, v170
	v_sub_f32_e32 v75, v75, v170
	v_sub_f32_e32 v76, v76, v170
	v_sub_f32_e32 v77, v77, v170
	v_sub_f32_e32 v78, v78, v170
	v_sub_f32_e32 v79, v79, v170
	v_sub_f32_e32 v80, v80, v170
	v_sub_f32_e32 v81, v81, v170
	v_sub_f32_e32 v82, v82, v170
	v_sub_f32_e32 v83, v83, v170
	v_sub_f32_e32 v84, v84, v170
	v_sub_f32_e32 v85, v85, v170
	v_sub_f32_e32 v86, v86, v170
	v_sub_f32_e32 v87, v87, v170
	v_sub_f32_e32 v88, v88, v170
	v_sub_f32_e32 v89, v89, v170
	v_sub_f32_e32 v90, v90, v170
	v_sub_f32_e32 v91, v91, v170
	v_sub_f32_e32 v92, v92, v170
	v_sub_f32_e32 v93, v93, v170
	v_sub_f32_e32 v94, v94, v170
	v_sub_f32_e32 v95, v95, v170
	s_waitcnt lgkmcnt(0)
	s_barrier
	s_cmp_eq_u32 s7, 0
	s_cbranch_scc1 .Lamla_tail
.Lamla_loop:
	ds_read_b128 v[136:139], v243 offset:0
	ds_read_b128 v[140:143], v243 offset:6656
	ds_read_b128 v[144:147], v243 offset:32
	ds_read_b128 v[148:151], v243 offset:6688
	s_waitcnt lgkmcnt(10)
	v_mfma_f32_32x32x16_bf16 v[0:15], v[176:179], v[96:99], v[0:15]
	v_max3_f32 v168, v64, v65, v66
	v_max3_f32 v170, v80, v81, v82
	v_max3_f32 v168, v168, v67, v68
	v_max3_f32 v170, v170, v83, v84
	v_max3_f32 v168, v168, v69, v70
	s_mov_b32 s55, s52
	s_mov_b32 s52, s53
	s_mov_b32 s53, s54
	s_mov_b32 s54, s55
	s_mov_b32 s9, 0
	s_waitcnt lgkmcnt(8)
	v_mfma_f32_32x32x16_bf16 v[16:31], v[180:183], v[96:99], v[16:31]
	v_max3_f32 v170, v170, v85, v86
	v_max3_f32 v168, v168, v71, v72
	v_max3_f32 v170, v170, v87, v88
	v_max3_f32 v168, v168, v73, v74
	global_load_dwordx4 v[152:155], v167, s[2:3]
	global_load_dwordx2 v[160:161], v165, s[10:11]
	global_load_dwordx4 v[156:159], v167, s[4:5]
	s_add_u32 s2, s2, 0x2000
	s_addc_u32 s3, s3, 0
	s_add_u32 s10, s10, 0x1000
	s_addc_u32 s11, s11, 0
	s_add_u32 s4, s4, 0x2000
	s_addc_u32 s5, s5, 0
	v_add_u32_e32 v162, s53, v240
	v_add_u32_e32 v164, s54, v241
	v_mfma_f32_16x16x32_bf16 v[234:237], v[246:249], v[96:99], v[234:237]
	v_max3_f32 v170, v170, v89, v90
	v_max3_f32 v168, v168, v75, v76
	v_max3_f32 v170, v170, v91, v92
	v_max3_f32 v168, v168, v77, v78
	s_waitcnt lgkmcnt(3)
	v_mfma_f32_32x32x16_bf16 v[32:47], v[136:139], v[112:115], v[218:233]
	v_max3_f32 v170, v170, v93, v94
	v_max3_f32 v168, v168, v170, v79
	v_max_f32_e32 v168, v168, v95
	v_cmp_lt_f32_e32 vcc, 0x41000000, v168
	s_cbranch_vccz .Lamla_nors_2
	v_mov_b32_e32 v170, v168
	s_nop 1
	v_permlane32_swap_b32_e32 v168, v170
	v_max_f32_e32 v168, v168, v170
	v_max_f32_e32 v170, 0, v168
	v_exp_f32_e64 v166, -v170
	v_sub_f32_e32 v64, v64, v170
	v_sub_f32_e32 v65, v65, v170
	v_sub_f32_e32 v66, v66, v170
	v_sub_f32_e32 v67, v67, v170
	v_sub_f32_e32 v68, v68, v170
	v_sub_f32_e32 v69, v69, v170
	v_sub_f32_e32 v70, v70, v170
	v_sub_f32_e32 v71, v71, v170
	v_sub_f32_e32 v72, v72, v170
	v_sub_f32_e32 v73, v73, v170
	v_sub_f32_e32 v74, v74, v170
	v_sub_f32_e32 v75, v75, v170
	v_sub_f32_e32 v76, v76, v170
	v_sub_f32_e32 v77, v77, v170
	v_sub_f32_e32 v78, v78, v170
	v_sub_f32_e32 v79, v79, v170
	v_sub_f32_e32 v80, v80, v170
	v_sub_f32_e32 v81, v81, v170
	v_sub_f32_e32 v82, v82, v170
	v_sub_f32_e32 v83, v83, v170
	v_sub_f32_e32 v84, v84, v170
	v_sub_f32_e32 v85, v85, v170
	v_sub_f32_e32 v86, v86, v170
	v_sub_f32_e32 v87, v87, v170
	v_sub_f32_e32 v88, v88, v170
	v_sub_f32_e32 v89, v89, v170
	v_sub_f32_e32 v90, v90, v170
	v_sub_f32_e32 v91, v91, v170
	v_sub_f32_e32 v92, v92, v170
	v_sub_f32_e32 v93, v93, v170
	v_sub_f32_e32 v94, v94, v170
	v_sub_f32_e32 v95, v95, v170
	s_mov_b32 s9, 1
.Lamla_nors_2:
	ds_read_b128 v[136:139], v243 offset:64
	ds_read_b64_tr_b16 v[192:193], v163 offset:3072
	ds_read_b64_tr_b16 v[194:195], v163 offset:4608
	s_waitcnt lgkmcnt(5)
	v_mfma_f32_32x32x16_bf16 v[48:63], v[140:143], v[112:115], v[218:233]
	v_exp_f32_e32 v64, v64
	v_exp_f32_e32 v80, v80
	ds_read_b128 v[140:143], v243 offset:6720
	ds_read_b64_tr_b16 v[196:197], v163 offset:3136
	ds_read_b64_tr_b16 v[198:199], v163 offset:4672
	v_mfma_f32_32x32x16_bf16 v[0:15], v[184:187], v[104:107], v[0:15]
	v_exp_f32_e32 v65, v65
	v_exp_f32_e32 v81, v81
	ds_read_b64_tr_b16 v[200:201], v163 offset:9216
	ds_read_b64_tr_b16 v[202:203], v163 offset:10752
	s_waitcnt lgkmcnt(9)
	v_mfma_f32_32x32x16_bf16 v[32:47], v[144:147], v[116:119], v[32:47]
	v_exp_f32_e32 v66, v66
	v_exp_f32_e32 v82, v82
	ds_read_b128 v[144:147], v243 offset:96
	ds_read_b64_tr_b16 v[204:205], v163 offset:9280
	ds_read_b64_tr_b16 v[206:207], v163 offset:10816
	v_mfma_f32_32x32x16_bf16 v[16:31], v[188:191], v[104:107], v[16:31]
	v_cvt_pk_bf16_f32 v96, v64, v65
	v_exp_f32_e32 v67, v67
	s_waitcnt lgkmcnt(11)
	v_mfma_f32_32x32x16_bf16 v[48:63], v[148:151], v[116:119], v[48:63]
	v_exp_f32_e32 v83, v83
	v_exp_f32_e32 v68, v68
	ds_read_b128 v[148:151], v243 offset:6752
	v_mfma_f32_16x16x32_bf16 v[234:237], v[246:249], v[104:107], v[234:237]
	v_cvt_pk_bf16_f32 v104, v80, v81
	v_exp_f32_e32 v84, v84
	v_cvt_pk_bf16_f32 v97, v66, v67
	v_cvt_pk_bf16_f32 v105, v82, v83
	s_waitcnt lgkmcnt(11)
	v_mfma_f32_32x32x16_bf16 v[32:47], v[136:139], v[120:123], v[32:47]
	v_exp_f32_e32 v69, v69
	v_exp_f32_e32 v85, v85
	ds_read_b128 v[136:139], v243 offset:128
	s_waitcnt lgkmcnt(9)
	v_mfma_f32_32x32x16_bf16 v[48:63], v[140:143], v[120:123], v[48:63]
	v_exp_f32_e32 v70, v70
	v_exp_f32_e32 v86, v86
	ds_read_b128 v[140:143], v243 offset:6784
	v_mfma_f32_32x32x16_bf16 v[0:15], v[192:195], v[100:103], v[0:15]
	v_cvt_pk_bf16_f32 v98, v68, v69
	v_cvt_pk_bf16_f32 v106, v84, v85
	v_exp_f32_e32 v71, v71
	v_exp_f32_e32 v87, v87
	s_waitcnt lgkmcnt(5)
	v_mfma_f32_32x32x16_bf16 v[32:47], v[144:147], v[124:127], v[32:47]
	v_exp_f32_e32 v72, v72
	v_exp_f32_e32 v88, v88
	ds_read_b128 v[144:147], v243 offset:160
	v_mfma_f32_32x32x16_bf16 v[16:31], v[196:199], v[100:103], v[16:31]
	v_cvt_pk_bf16_f32 v99, v70, v71
	v_cvt_pk_bf16_f32 v107, v86, v87
	v_exp_f32_e32 v73, v73
	s_waitcnt vmcnt(5)
	ds_write_b128 v238, v[208:211] offset:13312
	s_waitcnt vmcnt(4)
	ds_write_b64 v239, v[216:217] offset:13312
	s_waitcnt vmcnt(3)
	ds_write_b128 v164, v[212:215]
	s_waitcnt lgkmcnt(6)
	v_mfma_f32_32x32x16_bf16 v[48:63], v[148:151], v[124:127], v[48:63]
	v_exp_f32_e32 v89, v89
	v_exp_f32_e32 v74, v74
	ds_read_b128 v[148:151], v243 offset:6816
	v_mfma_f32_16x16x32_bf16 v[234:237], v[246:249], v[100:103], v[234:237]
	v_exp_f32_e32 v90, v90
	v_cvt_pk_bf16_f32 v100, v72, v73
	s_waitcnt lgkmcnt(6)
	v_mfma_f32_32x32x16_bf16 v[32:47], v[136:139], v[128:131], v[32:47]
	v_exp_f32_e32 v75, v75
	v_exp_f32_e32 v91, v91
	s_waitcnt lgkmcnt(5)
	v_mfma_f32_32x32x16_bf16 v[48:63], v[140:143], v[128:131], v[48:63]
	v_exp_f32_e32 v76, v76
	v_exp_f32_e32 v92, v92
	ds_read_b64_tr_b16 v[176:177], v162 offset:0
	ds_read_b64_tr_b16 v[178:179], v162 offset:1536
	v_mfma_f32_32x32x16_bf16 v[0:15], v[200:203], v[108:111], v[0:15]
	v_cvt_pk_bf16_f32 v101, v74, v75
	v_exp_f32_e32 v77, v77
	v_exp_f32_e32 v93, v93
	ds_read_b64_tr_b16 v[180:181], v162 offset:64
	ds_read_b64_tr_b16 v[182:183], v162 offset:1600
	s_waitcnt lgkmcnt(8)
	v_mfma_f32_32x32x16_bf16 v[32:47], v[144:147], v[132:135], v[32:47]
	v_exp_f32_e32 v78, v78
	v_exp_f32_e32 v94, v94
	ds_read_b64_tr_b16 v[184:185], v162 offset:6144
	ds_read_b64_tr_b16 v[186:187], v162 offset:7680
	v_mfma_f32_32x32x16_bf16 v[16:31], v[204:207], v[108:111], v[16:31]
	v_cvt_pk_bf16_f32 v102, v76, v77
	v_exp_f32_e32 v79, v79
	ds_read_b64_tr_b16 v[188:189], v162 offset:6208
	ds_read_b64_tr_b16 v[190:191], v162 offset:7744
	s_waitcnt lgkmcnt(8)
	v_mfma_f32_32x32x16_bf16 v[48:63], v[148:151], v[132:135], v[48:63]
	v_exp_f32_e32 v95, v95
	v_cvt_pk_bf16_f32 v103, v78, v79
	v_mfma_f32_16x16x32_bf16 v[234:237], v[246:249], v[108:111], v[234:237]
	v_cvt_pk_bf16_f32 v108, v88, v89
	v_cvt_pk_bf16_f32 v109, v90, v91
	v_cvt_pk_bf16_f32 v110, v92, v93
	v_cvt_pk_bf16_f32 v111, v94, v95
	s_cmp_lg_u32 s9, 0
	s_cbranch_scc0 .Lamla_noresc_3
	s_nop 15
	v_sub_f32_e32 v218, v218, v170
	v_sub_f32_e32 v219, v219, v170
	v_sub_f32_e32 v220, v220, v170
	v_sub_f32_e32 v221, v221, v170
	v_sub_f32_e32 v222, v222, v170
	v_sub_f32_e32 v223, v223, v170
	v_sub_f32_e32 v224, v224, v170
	v_sub_f32_e32 v225, v225, v170
	v_sub_f32_e32 v226, v226, v170
	v_sub_f32_e32 v227, v227, v170
	v_sub_f32_e32 v228, v228, v170
	v_sub_f32_e32 v229, v229, v170
	v_sub_f32_e32 v230, v230, v170
	v_sub_f32_e32 v231, v231, v170
	v_sub_f32_e32 v232, v232, v170
	v_sub_f32_e32 v233, v233, v170
	v_sub_f32_e32 v32, v32, v170
	v_sub_f32_e32 v33, v33, v170
	v_sub_f32_e32 v34, v34, v170
	v_sub_f32_e32 v35, v35, v170
	v_sub_f32_e32 v36, v36, v170
	v_sub_f32_e32 v37, v37, v170
	v_sub_f32_e32 v38, v38, v170
	v_sub_f32_e32 v39, v39, v170
	v_sub_f32_e32 v40, v40, v170
	v_sub_f32_e32 v41, v41, v170
	v_sub_f32_e32 v42, v42, v170
	v_sub_f32_e32 v43, v43, v170
	v_sub_f32_e32 v44, v44, v170
	v_sub_f32_e32 v45, v45, v170
	v_sub_f32_e32 v46, v46, v170
	v_sub_f32_e32 v47, v47, v170
	v_sub_f32_e32 v48, v48, v170
	v_sub_f32_e32 v49, v49, v170
	v_sub_f32_e32 v50, v50, v170
	v_sub_f32_e32 v51, v51, v170
	v_sub_f32_e32 v52, v52, v170
	v_sub_f32_e32 v53, v53, v170
	v_sub_f32_e32 v54, v54, v170
	v_sub_f32_e32 v55, v55, v170
	v_sub_f32_e32 v56, v56, v170
	v_sub_f32_e32 v57, v57, v170
	v_sub_f32_e32 v58, v58, v170
	v_sub_f32_e32 v59, v59, v170
	v_sub_f32_e32 v60, v60, v170
	v_sub_f32_e32 v61, v61, v170
	v_sub_f32_e32 v62, v62, v170
	v_sub_f32_e32 v63, v63, v170
	v_mul_f32_e32 v0, v0, v166
	v_mul_f32_e32 v1, v1, v166
	v_mul_f32_e32 v2, v2, v166
	v_mul_f32_e32 v3, v3, v166
	v_mul_f32_e32 v4, v4, v166
	v_mul_f32_e32 v5, v5, v166
	v_mul_f32_e32 v6, v6, v166
	v_mul_f32_e32 v7, v7, v166
	v_mul_f32_e32 v8, v8, v166
	v_mul_f32_e32 v9, v9, v166
	v_mul_f32_e32 v10, v10, v166
	v_mul_f32_e32 v11, v11, v166
	v_mul_f32_e32 v12, v12, v166
	v_mul_f32_e32 v13, v13, v166
	v_mul_f32_e32 v14, v14, v166
	v_mul_f32_e32 v15, v15, v166
	v_mul_f32_e32 v16, v16, v166
	v_mul_f32_e32 v17, v17, v166
	v_mul_f32_e32 v18, v18, v166
	v_mul_f32_e32 v19, v19, v166
	v_mul_f32_e32 v20, v20, v166
	v_mul_f32_e32 v21, v21, v166
	v_mul_f32_e32 v22, v22, v166
	v_mul_f32_e32 v23, v23, v166
	v_mul_f32_e32 v24, v24, v166
	v_mul_f32_e32 v25, v25, v166
	v_mul_f32_e32 v26, v26, v166
	v_mul_f32_e32 v27, v27, v166
	v_mul_f32_e32 v28, v28, v166
	v_mul_f32_e32 v29, v29, v166
	v_mul_f32_e32 v30, v30, v166
	v_mul_f32_e32 v31, v31, v166
	v_add_u32_e32 v170, 64, v175
	ds_bpermute_b32 v173, v170, v166
	v_mul_f32_e32 v234, v234, v166
	s_waitcnt lgkmcnt(0)
	v_mul_f32_e32 v235, v235, v173
.Lamla_noresc_3:
	s_nop 4
	s_barrier
	ds_read_b128 v[136:139], v243 offset:13312
	ds_read_b128 v[140:143], v243 offset:19968
	ds_read_b128 v[144:147], v243 offset:13344
	ds_read_b128 v[148:151], v243 offset:20000
	s_waitcnt lgkmcnt(10)
	v_mfma_f32_32x32x16_bf16 v[0:15], v[176:179], v[96:99], v[0:15]
	v_max3_f32 v168, v32, v33, v34
	v_max3_f32 v170, v48, v49, v50
	v_max3_f32 v168, v168, v35, v36
	v_max3_f32 v170, v170, v51, v52
	v_max3_f32 v168, v168, v37, v38
	s_mov_b32 s55, s52
	s_mov_b32 s52, s53
	s_mov_b32 s53, s54
	s_mov_b32 s54, s55
	s_mov_b32 s9, 0
	s_waitcnt lgkmcnt(8)
	v_mfma_f32_32x32x16_bf16 v[16:31], v[180:183], v[96:99], v[16:31]
	v_max3_f32 v170, v170, v53, v54
	v_max3_f32 v168, v168, v39, v40
	v_max3_f32 v170, v170, v55, v56
	v_max3_f32 v168, v168, v41, v42
	global_load_dwordx4 v[208:211], v167, s[2:3]
	global_load_dwordx2 v[216:217], v165, s[10:11]
	global_load_dwordx4 v[212:215], v167, s[4:5]
	s_add_u32 s2, s2, 0x2000
	s_addc_u32 s3, s3, 0
	s_add_u32 s10, s10, 0x1000
	s_addc_u32 s11, s11, 0
	s_add_u32 s4, s4, 0x2000
	s_addc_u32 s5, s5, 0
	v_add_u32_e32 v163, s53, v240
	v_add_u32_e32 v164, s54, v241
	v_mfma_f32_16x16x32_bf16 v[234:237], v[246:249], v[96:99], v[234:237]
	v_max3_f32 v170, v170, v57, v58
	v_max3_f32 v168, v168, v43, v44
	v_max3_f32 v170, v170, v59, v60
	v_max3_f32 v168, v168, v45, v46
	s_waitcnt lgkmcnt(3)
	v_mfma_f32_32x32x16_bf16 v[64:79], v[136:139], v[112:115], v[218:233]
	v_max3_f32 v170, v170, v61, v62
	v_max3_f32 v168, v168, v170, v47
	v_max_f32_e32 v168, v168, v63
	v_cmp_lt_f32_e32 vcc, 0x41000000, v168
	s_cbranch_vccz .Lamla_nors_4
	v_mov_b32_e32 v170, v168
	s_nop 1
	v_permlane32_swap_b32_e32 v168, v170
	v_max_f32_e32 v168, v168, v170
	v_max_f32_e32 v170, 0, v168
	v_exp_f32_e64 v166, -v170
	v_sub_f32_e32 v32, v32, v170
	v_sub_f32_e32 v33, v33, v170
	v_sub_f32_e32 v34, v34, v170
	v_sub_f32_e32 v35, v35, v170
	v_sub_f32_e32 v36, v36, v170
	v_sub_f32_e32 v37, v37, v170
	v_sub_f32_e32 v38, v38, v170
	v_sub_f32_e32 v39, v39, v170
	v_sub_f32_e32 v40, v40, v170
	v_sub_f32_e32 v41, v41, v170
	v_sub_f32_e32 v42, v42, v170
	v_sub_f32_e32 v43, v43, v170
	v_sub_f32_e32 v44, v44, v170
	v_sub_f32_e32 v45, v45, v170
	v_sub_f32_e32 v46, v46, v170
	v_sub_f32_e32 v47, v47, v170
	v_sub_f32_e32 v48, v48, v170
	v_sub_f32_e32 v49, v49, v170
	v_sub_f32_e32 v50, v50, v170
	v_sub_f32_e32 v51, v51, v170
	v_sub_f32_e32 v52, v52, v170
	v_sub_f32_e32 v53, v53, v170
	v_sub_f32_e32 v54, v54, v170
	v_sub_f32_e32 v55, v55, v170
	v_sub_f32_e32 v56, v56, v170
	v_sub_f32_e32 v57, v57, v170
	v_sub_f32_e32 v58, v58, v170
	v_sub_f32_e32 v59, v59, v170
	v_sub_f32_e32 v60, v60, v170
	v_sub_f32_e32 v61, v61, v170
	v_sub_f32_e32 v62, v62, v170
	v_sub_f32_e32 v63, v63, v170
	s_mov_b32 s9, 1
.Lamla_nors_4:
	ds_read_b128 v[136:139], v243 offset:13376
	ds_read_b64_tr_b16 v[192:193], v162 offset:3072
	ds_read_b64_tr_b16 v[194:195], v162 offset:4608
	s_waitcnt lgkmcnt(5)
	v_mfma_f32_32x32x16_bf16 v[80:95], v[140:143], v[112:115], v[218:233]
	v_exp_f32_e32 v32, v32
	v_exp_f32_e32 v48, v48
	ds_read_b128 v[140:143], v243 offset:20032
	ds_read_b64_tr_b16 v[196:197], v162 offset:3136
	ds_read_b64_tr_b16 v[198:199], v162 offset:4672
	v_mfma_f32_32x32x16_bf16 v[0:15], v[184:187], v[104:107], v[0:15]
	v_exp_f32_e32 v33, v33
	v_exp_f32_e32 v49, v49
	ds_read_b64_tr_b16 v[200:201], v162 offset:9216
	ds_read_b64_tr_b16 v[202:203], v162 offset:10752
	s_waitcnt lgkmcnt(9)
	v_mfma_f32_32x32x16_bf16 v[64:79], v[144:147], v[116:119], v[64:79]
	v_exp_f32_e32 v34, v34
	v_exp_f32_e32 v50, v50
	ds_read_b128 v[144:147], v243 offset:13408
	ds_read_b64_tr_b16 v[204:205], v162 offset:9280
	ds_read_b64_tr_b16 v[206:207], v162 offset:10816
	v_mfma_f32_32x32x16_bf16 v[16:31], v[188:191], v[104:107], v[16:31]
	v_cvt_pk_bf16_f32 v96, v32, v33
	v_exp_f32_e32 v35, v35
	s_waitcnt lgkmcnt(11)
	v_mfma_f32_32x32x16_bf16 v[80:95], v[148:151], v[116:119], v[80:95]
	v_exp_f32_e32 v51, v51
	v_exp_f32_e32 v36, v36
	ds_read_b128 v[148:151], v243 offset:20064
	v_mfma_f32_16x16x32_bf16 v[234:237], v[246:249], v[104:107], v[234:237]
	v_cvt_pk_bf16_f32 v104, v48, v49
	v_exp_f32_e32 v52, v52
	v_cvt_pk_bf16_f32 v97, v34, v35
	v_cvt_pk_bf16_f32 v105, v50, v51
	s_waitcnt lgkmcnt(11)
	v_mfma_f32_32x32x16_bf16 v[64:79], v[136:139], v[120:123], v[64:79]
	v_exp_f32_e32 v37, v37
	v_exp_f32_e32 v53, v53
	ds_read_b128 v[136:139], v243 offset:13440
	s_waitcnt lgkmcnt(9)
	v_mfma_f32_32x32x16_bf16 v[80:95], v[140:143], v[120:123], v[80:95]
	v_exp_f32_e32 v38, v38
	v_exp_f32_e32 v54, v54
	ds_read_b128 v[140:143], v243 offset:20096
	v_mfma_f32_32x32x16_bf16 v[0:15], v[192:195], v[100:103], v[0:15]
	v_cvt_pk_bf16_f32 v98, v36, v37
	v_cvt_pk_bf16_f32 v106, v52, v53
	v_exp_f32_e32 v39, v39
	v_exp_f32_e32 v55, v55
	s_waitcnt lgkmcnt(5)
	v_mfma_f32_32x32x16_bf16 v[64:79], v[144:147], v[124:127], v[64:79]
	v_exp_f32_e32 v40, v40
	v_exp_f32_e32 v56, v56
	ds_read_b128 v[144:147], v243 offset:13472
	v_mfma_f32_32x32x16_bf16 v[16:31], v[196:199], v[100:103], v[16:31]
	v_cvt_pk_bf16_f32 v99, v38, v39
	v_cvt_pk_bf16_f32 v107, v54, v55
	v_exp_f32_e32 v41, v41
	s_waitcnt vmcnt(5)
	ds_write_b128 v238, v[152:155]
	s_waitcnt vmcnt(4)
	ds_write_b64 v239, v[160:161]
	s_waitcnt vmcnt(3)
	ds_write_b128 v164, v[156:159]
	s_waitcnt lgkmcnt(6)
	v_mfma_f32_32x32x16_bf16 v[80:95], v[148:151], v[124:127], v[80:95]
	v_exp_f32_e32 v57, v57
	v_exp_f32_e32 v42, v42
	ds_read_b128 v[148:151], v243 offset:20128
	v_mfma_f32_16x16x32_bf16 v[234:237], v[246:249], v[100:103], v[234:237]
	v_exp_f32_e32 v58, v58
	v_cvt_pk_bf16_f32 v100, v40, v41
	s_waitcnt lgkmcnt(6)
	v_mfma_f32_32x32x16_bf16 v[64:79], v[136:139], v[128:131], v[64:79]
	v_exp_f32_e32 v43, v43
	v_exp_f32_e32 v59, v59
	s_waitcnt lgkmcnt(5)
	v_mfma_f32_32x32x16_bf16 v[80:95], v[140:143], v[128:131], v[80:95]
	v_exp_f32_e32 v44, v44
	v_exp_f32_e32 v60, v60
	ds_read_b64_tr_b16 v[176:177], v163 offset:0
	ds_read_b64_tr_b16 v[178:179], v163 offset:1536
	v_mfma_f32_32x32x16_bf16 v[0:15], v[200:203], v[108:111], v[0:15]
	v_cvt_pk_bf16_f32 v101, v42, v43
	v_exp_f32_e32 v45, v45
	v_exp_f32_e32 v61, v61
	ds_read_b64_tr_b16 v[180:181], v163 offset:64
	ds_read_b64_tr_b16 v[182:183], v163 offset:1600
	s_waitcnt lgkmcnt(8)
	v_mfma_f32_32x32x16_bf16 v[64:79], v[144:147], v[132:135], v[64:79]
	v_exp_f32_e32 v46, v46
	v_exp_f32_e32 v62, v62
	ds_read_b64_tr_b16 v[184:185], v163 offset:6144
	ds_read_b64_tr_b16 v[186:187], v163 offset:7680
	v_mfma_f32_32x32x16_bf16 v[16:31], v[204:207], v[108:111], v[16:31]
	v_cvt_pk_bf16_f32 v102, v44, v45
	v_exp_f32_e32 v47, v47
	ds_read_b64_tr_b16 v[188:189], v163 offset:6208
	ds_read_b64_tr_b16 v[190:191], v163 offset:7744
	s_waitcnt lgkmcnt(8)
	v_mfma_f32_32x32x16_bf16 v[80:95], v[148:151], v[132:135], v[80:95]
	v_exp_f32_e32 v63, v63
	v_cvt_pk_bf16_f32 v103, v46, v47
	v_mfma_f32_16x16x32_bf16 v[234:237], v[246:249], v[108:111], v[234:237]
	v_cvt_pk_bf16_f32 v108, v56, v57
	v_cvt_pk_bf16_f32 v109, v58, v59
	v_cvt_pk_bf16_f32 v110, v60, v61
	v_cvt_pk_bf16_f32 v111, v62, v63
	s_cmp_lg_u32 s9, 0
	s_cbranch_scc0 .Lamla_noresc_5
; #define AT_STEP(SC0, SC1, SN0, SN1, t, DOK, DOV) do { \
;             if (DOK) AT_GLOADK(((t) + 2) * 64); \
;             if (DOV) { AT_GLOADV(((t) + 1) * 64); AT_QK(SN0, SN1, ((t) + 1) & 1); } \
;             AT_SMPV(SC0, SC1, (t) & 1); \
;             if (DOK) AT_WRITEK((t) & 1); \
;             if (DOV) AT_WRITEV(((t) + 1) & 1); \
;             __syncthreads(); } while (0)
; template <bool MLA>
; DI void attn_phase(const int TID, const int BID, LAS unsigned char* lds, const Params& p, bool need_ctx) {
;     ...
;         AT_STEP(sa0, sa1, sb0, sb1, t, false, true);
;         AT_STEP(sb0, sb1, sa0, sa1, t + 1, false, false);
	s_nop 15
	v_sub_f32_e32 v218, v218, v170
	v_sub_f32_e32 v219, v219, v170
	v_sub_f32_e32 v220, v220, v170
	v_sub_f32_e32 v221, v221, v170
	v_sub_f32_e32 v222, v222, v170
	v_sub_f32_e32 v223, v223, v170
	v_sub_f32_e32 v224, v224, v170
	v_sub_f32_e32 v225, v225, v170
	v_sub_f32_e32 v226, v226, v170
	v_sub_f32_e32 v227, v227, v170
	v_sub_f32_e32 v228, v228, v170
	v_sub_f32_e32 v229, v229, v170
	v_sub_f32_e32 v230, v230, v170
	v_sub_f32_e32 v231, v231, v170
	v_sub_f32_e32 v232, v232, v170
	v_sub_f32_e32 v233, v233, v170
	v_sub_f32_e32 v64, v64, v170
	v_sub_f32_e32 v65, v65, v170
	v_sub_f32_e32 v66, v66, v170
	v_sub_f32_e32 v67, v67, v170
	v_sub_f32_e32 v68, v68, v170
	v_sub_f32_e32 v69, v69, v170
	v_sub_f32_e32 v70, v70, v170
	v_sub_f32_e32 v71, v71, v170
	v_sub_f32_e32 v72, v72, v170
	v_sub_f32_e32 v73, v73, v170
	v_sub_f32_e32 v74, v74, v170
	v_sub_f32_e32 v75, v75, v170
	v_sub_f32_e32 v76, v76, v170
	v_sub_f32_e32 v77, v77, v170
	v_sub_f32_e32 v78, v78, v170
	v_sub_f32_e32 v79, v79, v170
	v_sub_f32_e32 v80, v80, v170
	v_sub_f32_e32 v81, v81, v170
	v_sub_f32_e32 v82, v82, v170
	v_sub_f32_e32 v83, v83, v170
	v_sub_f32_e32 v84, v84, v170
	v_sub_f32_e32 v85, v85, v170
	v_sub_f32_e32 v86, v86, v170
	v_sub_f32_e32 v87, v87, v170
	v_sub_f32_e32 v88, v88, v170
	v_sub_f32_e32 v89, v89, v170
	v_sub_f32_e32 v90, v90, v170
	v_sub_f32_e32 v91, v91, v170
	v_sub_f32_e32 v92, v92, v170
	v_sub_f32_e32 v93, v93, v170
	v_sub_f32_e32 v94, v94, v170
	v_sub_f32_e32 v95, v95, v170
	v_mul_f32_e32 v0, v0, v166
	v_mul_f32_e32 v1, v1, v166
	v_mul_f32_e32 v2, v2, v166
	v_mul_f32_e32 v3, v3, v166
	v_mul_f32_e32 v4, v4, v166
	v_mul_f32_e32 v5, v5, v166
	v_mul_f32_e32 v6, v6, v166
	v_mul_f32_e32 v7, v7, v166
	v_mul_f32_e32 v8, v8, v166
	v_mul_f32_e32 v9, v9, v166
	v_mul_f32_e32 v10, v10, v166
	v_mul_f32_e32 v11, v11, v166
	v_mul_f32_e32 v12, v12, v166
	v_mul_f32_e32 v13, v13, v166
	v_mul_f32_e32 v14, v14, v166
	v_mul_f32_e32 v15, v15, v166
	v_mul_f32_e32 v16, v16, v166
	v_mul_f32_e32 v17, v17, v166
	v_mul_f32_e32 v18, v18, v166
	v_mul_f32_e32 v19, v19, v166
	v_mul_f32_e32 v20, v20, v166
	v_mul_f32_e32 v21, v21, v166
	v_mul_f32_e32 v22, v22, v166
	v_mul_f32_e32 v23, v23, v166
	v_mul_f32_e32 v24, v24, v166
	v_mul_f32_e32 v25, v25, v166
	v_mul_f32_e32 v26, v26, v166
	v_mul_f32_e32 v27, v27, v166
	v_mul_f32_e32 v28, v28, v166
	v_mul_f32_e32 v29, v29, v166
	v_mul_f32_e32 v30, v30, v166
	v_mul_f32_e32 v31, v31, v166
	v_add_u32_e32 v170, 64, v175
	ds_bpermute_b32 v173, v170, v166
	v_mul_f32_e32 v234, v234, v166
	s_waitcnt lgkmcnt(0)
	v_mul_f32_e32 v235, v235, v173
.Lamla_noresc_5:
	s_nop 4
	s_barrier
	s_add_i32 s7, s7, -1
	s_cmp_lg_u32 s7, 0
	s_cbranch_scc1 .Lamla_loop
.Lamla_tail:
	ds_read_b128 v[136:139], v243 offset:0
	ds_read_b128 v[140:143], v243 offset:6656
	ds_read_b128 v[144:147], v243 offset:32
	ds_read_b128 v[148:151], v243 offset:6688
	s_waitcnt lgkmcnt(10)
	v_mfma_f32_32x32x16_bf16 v[0:15], v[176:179], v[96:99], v[0:15]
	v_max3_f32 v168, v64, v65, v66
	v_max3_f32 v170, v80, v81, v82
	v_max3_f32 v168, v168, v67, v68
	v_max3_f32 v170, v170, v83, v84
	v_max3_f32 v168, v168, v69, v70
	s_mov_b32 s55, s52
	s_mov_b32 s52, s53
	s_mov_b32 s53, s54
	s_mov_b32 s54, s55
	s_mov_b32 s9, 0
	s_waitcnt lgkmcnt(8)
	v_mfma_f32_32x32x16_bf16 v[16:31], v[180:183], v[96:99], v[16:31]
	v_max3_f32 v170, v170, v85, v86
	v_max3_f32 v168, v168, v71, v72
	v_max3_f32 v170, v170, v87, v88
	v_max3_f32 v168, v168, v73, v74
	global_load_dwordx4 v[156:159], v167, s[4:5]
	s_add_u32 s4, s4, 0x2000
	s_addc_u32 s5, s5, 0
	v_add_u32_e32 v162, s53, v240
	v_add_u32_e32 v164, s54, v241
	v_mfma_f32_16x16x32_bf16 v[234:237], v[246:249], v[96:99], v[234:237]
	v_max3_f32 v170, v170, v89, v90
	v_max3_f32 v168, v168, v75, v76
	v_max3_f32 v170, v170, v91, v92
	v_max3_f32 v168, v168, v77, v78
	s_waitcnt lgkmcnt(3)
	v_mfma_f32_32x32x16_bf16 v[32:47], v[136:139], v[112:115], v[218:233]
	v_max3_f32 v170, v170, v93, v94
	v_max3_f32 v168, v168, v170, v79
	v_max_f32_e32 v168, v168, v95
	v_cmp_lt_f32_e32 vcc, 0x41000000, v168
	s_cbranch_vccz .Lamla_nors_6
	v_mov_b32_e32 v170, v168
	s_nop 1
	v_permlane32_swap_b32_e32 v168, v170
	v_max_f32_e32 v168, v168, v170
	v_max_f32_e32 v170, 0, v168
	v_exp_f32_e64 v166, -v170
	v_sub_f32_e32 v64, v64, v170
	v_sub_f32_e32 v65, v65, v170
	v_sub_f32_e32 v66, v66, v170
	v_sub_f32_e32 v67, v67, v170
	v_sub_f32_e32 v68, v68, v170
	v_sub_f32_e32 v69, v69, v170
	v_sub_f32_e32 v70, v70, v170
	v_sub_f32_e32 v71, v71, v170
	v_sub_f32_e32 v72, v72, v170
	v_sub_f32_e32 v73, v73, v170
	v_sub_f32_e32 v74, v74, v170
	v_sub_f32_e32 v75, v75, v170
	v_sub_f32_e32 v76, v76, v170
	v_sub_f32_e32 v77, v77, v170
	v_sub_f32_e32 v78, v78, v170
	v_sub_f32_e32 v79, v79, v170
	v_sub_f32_e32 v80, v80, v170
	v_sub_f32_e32 v81, v81, v170
	v_sub_f32_e32 v82, v82, v170
	v_sub_f32_e32 v83, v83, v170
	v_sub_f32_e32 v84, v84, v170
	v_sub_f32_e32 v85, v85, v170
	v_sub_f32_e32 v86, v86, v170
	v_sub_f32_e32 v87, v87, v170
	v_sub_f32_e32 v88, v88, v170
	v_sub_f32_e32 v89, v89, v170
	v_sub_f32_e32 v90, v90, v170
	v_sub_f32_e32 v91, v91, v170
	v_sub_f32_e32 v92, v92, v170
	v_sub_f32_e32 v93, v93, v170
	v_sub_f32_e32 v94, v94, v170
	v_sub_f32_e32 v95, v95, v170
	s_mov_b32 s9, 1
.Lamla_nors_6:
	ds_read_b128 v[136:139], v243 offset:64
	ds_read_b64_tr_b16 v[192:193], v163 offset:3072
	ds_read_b64_tr_b16 v[194:195], v163 offset:4608
	s_waitcnt lgkmcnt(5)
	v_mfma_f32_32x32x16_bf16 v[48:63], v[140:143], v[112:115], v[218:233]
	v_exp_f32_e32 v64, v64
	v_exp_f32_e32 v80, v80
	ds_read_b128 v[140:143], v243 offset:6720
	ds_read_b64_tr_b16 v[196:197], v163 offset:3136
	ds_read_b64_tr_b16 v[198:199], v163 offset:4672
	v_mfma_f32_32x32x16_bf16 v[0:15], v[184:187], v[104:107], v[0:15]
	v_exp_f32_e32 v65, v65
	v_exp_f32_e32 v81, v81
	ds_read_b64_tr_b16 v[200:201], v163 offset:9216
	ds_read_b64_tr_b16 v[202:203], v163 offset:10752
	s_waitcnt lgkmcnt(9)
	v_mfma_f32_32x32x16_bf16 v[32:47], v[144:147], v[116:119], v[32:47]
	v_exp_f32_e32 v66, v66
	v_exp_f32_e32 v82, v82
	ds_read_b128 v[144:147], v243 offset:96
	ds_read_b64_tr_b16 v[204:205], v163 offset:9280
	ds_read_b64_tr_b16 v[206:207], v163 offset:10816
	v_mfma_f32_32x32x16_bf16 v[16:31], v[188:191], v[104:107], v[16:31]
	v_cvt_pk_bf16_f32 v96, v64, v65
	v_exp_f32_e32 v67, v67
	s_waitcnt lgkmcnt(11)
	v_mfma_f32_32x32x16_bf16 v[48:63], v[148:151], v[116:119], v[48:63]
	v_exp_f32_e32 v83, v83
	v_exp_f32_e32 v68, v68
	ds_read_b128 v[148:151], v243 offset:6752
	v_mfma_f32_16x16x32_bf16 v[234:237], v[246:249], v[104:107], v[234:237]
	v_cvt_pk_bf16_f32 v104, v80, v81
	v_exp_f32_e32 v84, v84
	v_cvt_pk_bf16_f32 v97, v66, v67
	v_cvt_pk_bf16_f32 v105, v82, v83
	s_waitcnt lgkmcnt(11)
	v_mfma_f32_32x32x16_bf16 v[32:47], v[136:139], v[120:123], v[32:47]
	v_exp_f32_e32 v69, v69
	v_exp_f32_e32 v85, v85
	ds_read_b128 v[136:139], v243 offset:128
	s_waitcnt lgkmcnt(9)
	v_mfma_f32_32x32x16_bf16 v[48:63], v[140:143], v[120:123], v[48:63]
	v_exp_f32_e32 v70, v70
	v_exp_f32_e32 v86, v86
	ds_read_b128 v[140:143], v243 offset:6784
	v_mfma_f32_32x32x16_bf16 v[0:15], v[192:195], v[100:103], v[0:15]
	v_cvt_pk_bf16_f32 v98, v68, v69
	v_cvt_pk_bf16_f32 v106, v84, v85
	v_exp_f32_e32 v71, v71
	v_exp_f32_e32 v87, v87
	s_waitcnt lgkmcnt(5)
	v_mfma_f32_32x32x16_bf16 v[32:47], v[144:147], v[124:127], v[32:47]
	v_exp_f32_e32 v72, v72
	v_exp_f32_e32 v88, v88
	ds_read_b128 v[144:147], v243 offset:160
	v_mfma_f32_32x32x16_bf16 v[16:31], v[196:199], v[100:103], v[16:31]
	v_cvt_pk_bf16_f32 v99, v70, v71
	v_cvt_pk_bf16_f32 v107, v86, v87
	v_exp_f32_e32 v73, v73
	s_waitcnt vmcnt(3)
	ds_write_b128 v238, v[208:211] offset:13312
	s_waitcnt vmcnt(2)
	ds_write_b64 v239, v[216:217] offset:13312
	s_waitcnt vmcnt(1)
	ds_write_b128 v164, v[212:215]
	s_waitcnt lgkmcnt(6)
	v_mfma_f32_32x32x16_bf16 v[48:63], v[148:151], v[124:127], v[48:63]
	v_exp_f32_e32 v89, v89
	v_exp_f32_e32 v74, v74
	ds_read_b128 v[148:151], v243 offset:6816
	v_mfma_f32_16x16x32_bf16 v[234:237], v[246:249], v[100:103], v[234:237]
	v_exp_f32_e32 v90, v90
	v_cvt_pk_bf16_f32 v100, v72, v73
	s_waitcnt lgkmcnt(6)
	v_mfma_f32_32x32x16_bf16 v[32:47], v[136:139], v[128:131], v[32:47]
	v_exp_f32_e32 v75, v75
	v_exp_f32_e32 v91, v91
	s_waitcnt lgkmcnt(5)
	v_mfma_f32_32x32x16_bf16 v[48:63], v[140:143], v[128:131], v[48:63]
	v_exp_f32_e32 v76, v76
	v_exp_f32_e32 v92, v92
	ds_read_b64_tr_b16 v[176:177], v162 offset:0
	ds_read_b64_tr_b16 v[178:179], v162 offset:1536
	v_mfma_f32_32x32x16_bf16 v[0:15], v[200:203], v[108:111], v[0:15]
	v_cvt_pk_bf16_f32 v101, v74, v75
	v_exp_f32_e32 v77, v77
	v_exp_f32_e32 v93, v93
	ds_read_b64_tr_b16 v[180:181], v162 offset:64
	ds_read_b64_tr_b16 v[182:183], v162 offset:1600
	s_waitcnt lgkmcnt(8)
	v_mfma_f32_32x32x16_bf16 v[32:47], v[144:147], v[132:135], v[32:47]
	v_exp_f32_e32 v78, v78
	v_exp_f32_e32 v94, v94
	ds_read_b64_tr_b16 v[184:185], v162 offset:6144
	ds_read_b64_tr_b16 v[186:187], v162 offset:7680
	v_mfma_f32_32x32x16_bf16 v[16:31], v[204:207], v[108:111], v[16:31]
	v_cvt_pk_bf16_f32 v102, v76, v77
	v_exp_f32_e32 v79, v79
	ds_read_b64_tr_b16 v[188:189], v162 offset:6208
	ds_read_b64_tr_b16 v[190:191], v162 offset:7744
	s_waitcnt lgkmcnt(8)
	v_mfma_f32_32x32x16_bf16 v[48:63], v[148:151], v[132:135], v[48:63]
	v_exp_f32_e32 v95, v95
	v_cvt_pk_bf16_f32 v103, v78, v79
	v_mfma_f32_16x16x32_bf16 v[234:237], v[246:249], v[108:111], v[234:237]
	v_cvt_pk_bf16_f32 v108, v88, v89
	v_cvt_pk_bf16_f32 v109, v90, v91
	v_cvt_pk_bf16_f32 v110, v92, v93
	v_cvt_pk_bf16_f32 v111, v94, v95
	s_cmp_lg_u32 s9, 0
	s_cbranch_scc0 .Lamla_noresc_7
	s_nop 15
	v_sub_f32_e32 v218, v218, v170
	v_sub_f32_e32 v219, v219, v170
	v_sub_f32_e32 v220, v220, v170
	v_sub_f32_e32 v221, v221, v170
	v_sub_f32_e32 v222, v222, v170
	v_sub_f32_e32 v223, v223, v170
	v_sub_f32_e32 v224, v224, v170
	v_sub_f32_e32 v225, v225, v170
	v_sub_f32_e32 v226, v226, v170
	v_sub_f32_e32 v227, v227, v170
	v_sub_f32_e32 v228, v228, v170
	v_sub_f32_e32 v229, v229, v170
	v_sub_f32_e32 v230, v230, v170
	v_sub_f32_e32 v231, v231, v170
	v_sub_f32_e32 v232, v232, v170
	v_sub_f32_e32 v233, v233, v170
	v_sub_f32_e32 v32, v32, v170
	v_sub_f32_e32 v33, v33, v170
	v_sub_f32_e32 v34, v34, v170
	v_sub_f32_e32 v35, v35, v170
	v_sub_f32_e32 v36, v36, v170
	v_sub_f32_e32 v37, v37, v170
	v_sub_f32_e32 v38, v38, v170
	v_sub_f32_e32 v39, v39, v170
	v_sub_f32_e32 v40, v40, v170
	v_sub_f32_e32 v41, v41, v170
	v_sub_f32_e32 v42, v42, v170
	v_sub_f32_e32 v43, v43, v170
	v_sub_f32_e32 v44, v44, v170
	v_sub_f32_e32 v45, v45, v170
	v_sub_f32_e32 v46, v46, v170
	v_sub_f32_e32 v47, v47, v170
	v_sub_f32_e32 v48, v48, v170
	v_sub_f32_e32 v49, v49, v170
	v_sub_f32_e32 v50, v50, v170
	v_sub_f32_e32 v51, v51, v170
	v_sub_f32_e32 v52, v52, v170
	v_sub_f32_e32 v53, v53, v170
	v_sub_f32_e32 v54, v54, v170
	v_sub_f32_e32 v55, v55, v170
	v_sub_f32_e32 v56, v56, v170
	v_sub_f32_e32 v57, v57, v170
	v_sub_f32_e32 v58, v58, v170
	v_sub_f32_e32 v59, v59, v170
	v_sub_f32_e32 v60, v60, v170
	v_sub_f32_e32 v61, v61, v170
	v_sub_f32_e32 v62, v62, v170
	v_sub_f32_e32 v63, v63, v170
	v_mul_f32_e32 v0, v0, v166
	v_mul_f32_e32 v1, v1, v166
	v_mul_f32_e32 v2, v2, v166
	v_mul_f32_e32 v3, v3, v166
	v_mul_f32_e32 v4, v4, v166
	v_mul_f32_e32 v5, v5, v166
	v_mul_f32_e32 v6, v6, v166
	v_mul_f32_e32 v7, v7, v166
	v_mul_f32_e32 v8, v8, v166
	v_mul_f32_e32 v9, v9, v166
	v_mul_f32_e32 v10, v10, v166
	v_mul_f32_e32 v11, v11, v166
	v_mul_f32_e32 v12, v12, v166
	v_mul_f32_e32 v13, v13, v166
	v_mul_f32_e32 v14, v14, v166
	v_mul_f32_e32 v15, v15, v166
	v_mul_f32_e32 v16, v16, v166
	v_mul_f32_e32 v17, v17, v166
	v_mul_f32_e32 v18, v18, v166
	v_mul_f32_e32 v19, v19, v166
	v_mul_f32_e32 v20, v20, v166
	v_mul_f32_e32 v21, v21, v166
	v_mul_f32_e32 v22, v22, v166
	v_mul_f32_e32 v23, v23, v166
	v_mul_f32_e32 v24, v24, v166
	v_mul_f32_e32 v25, v25, v166
	v_mul_f32_e32 v26, v26, v166
	v_mul_f32_e32 v27, v27, v166
	v_mul_f32_e32 v28, v28, v166
	v_mul_f32_e32 v29, v29, v166
	v_mul_f32_e32 v30, v30, v166
	v_mul_f32_e32 v31, v31, v166
	v_add_u32_e32 v170, 64, v175
	ds_bpermute_b32 v173, v170, v166
	v_mul_f32_e32 v234, v234, v166
	s_waitcnt lgkmcnt(0)
	v_mul_f32_e32 v235, v235, v173
; #define AT_STEP(SC0, SC1, SN0, SN1, t, DOK, DOV) do { \
;             if (DOK) AT_GLOADK(((t) + 2) * 64); \
;             if (DOV) { AT_GLOADV(((t) + 1) * 64); AT_QK(SN0, SN1, ((t) + 1) & 1); } \
;             AT_SMPV(SC0, SC1, (t) & 1); \
;             if (DOK) AT_WRITEK((t) & 1); \
;             if (DOV) AT_WRITEV(((t) + 1) & 1); \
;             __syncthreads(); } while (0)
; template <bool MLA>
; DI void attn_phase(const int TID, const int BID, LAS unsigned char* lds, const Params& p, bool need_ctx) {
;     ...
;         AT_STEP(sa0, sa1, sb0, sb1, t, false, true);
;         AT_STEP(sb0, sb1, sa0, sa1, t + 1, false, false);
.Lamla_noresc_7:
	s_nop 4
	s_barrier
	ds_read_b128 v[136:139], v243 offset:13312
	ds_read_b128 v[140:143], v243 offset:19968
	ds_read_b128 v[144:147], v243 offset:13344
	ds_read_b128 v[148:151], v243 offset:20000
	s_waitcnt lgkmcnt(10)
	v_mfma_f32_32x32x16_bf16 v[0:15], v[176:179], v[96:99], v[0:15]
	v_max3_f32 v168, v32, v33, v34
	v_max3_f32 v170, v48, v49, v50
	v_max3_f32 v168, v168, v35, v36
	v_max3_f32 v170, v170, v51, v52
	v_max3_f32 v168, v168, v37, v38
	s_mov_b32 s55, s52
	s_mov_b32 s52, s53
	s_mov_b32 s53, s54
	s_mov_b32 s54, s55
	s_mov_b32 s9, 0
	s_waitcnt lgkmcnt(8)
	v_mfma_f32_32x32x16_bf16 v[16:31], v[180:183], v[96:99], v[16:31]
	v_max3_f32 v170, v170, v53, v54
	v_max3_f32 v168, v168, v39, v40
	v_max3_f32 v170, v170, v55, v56
	v_max3_f32 v168, v168, v41, v42
	v_add_u32_e32 v163, s53, v240
	v_add_u32_e32 v164, s54, v241
	v_mfma_f32_16x16x32_bf16 v[234:237], v[246:249], v[96:99], v[234:237]
	v_max3_f32 v170, v170, v57, v58
	v_max3_f32 v168, v168, v43, v44
	v_max3_f32 v170, v170, v59, v60
	v_max3_f32 v168, v168, v45, v46
	s_waitcnt lgkmcnt(3)
	v_mfma_f32_32x32x16_bf16 v[64:79], v[136:139], v[112:115], v[218:233]
	v_max3_f32 v170, v170, v61, v62
	v_max3_f32 v168, v168, v170, v47
	v_max_f32_e32 v168, v168, v63
	v_cmp_lt_f32_e32 vcc, 0x41000000, v168
	s_cbranch_vccz .Lamla_nors_8
	v_mov_b32_e32 v170, v168
	s_nop 1
	v_permlane32_swap_b32_e32 v168, v170
	v_max_f32_e32 v168, v168, v170
	v_max_f32_e32 v170, 0, v168
	v_exp_f32_e64 v166, -v170
	v_sub_f32_e32 v32, v32, v170
	v_sub_f32_e32 v33, v33, v170
	v_sub_f32_e32 v34, v34, v170
	v_sub_f32_e32 v35, v35, v170
	v_sub_f32_e32 v36, v36, v170
	v_sub_f32_e32 v37, v37, v170
	v_sub_f32_e32 v38, v38, v170
	v_sub_f32_e32 v39, v39, v170
	v_sub_f32_e32 v40, v40, v170
	v_sub_f32_e32 v41, v41, v170
	v_sub_f32_e32 v42, v42, v170
	v_sub_f32_e32 v43, v43, v170
	v_sub_f32_e32 v44, v44, v170
	v_sub_f32_e32 v45, v45, v170
	v_sub_f32_e32 v46, v46, v170
	v_sub_f32_e32 v47, v47, v170
	v_sub_f32_e32 v48, v48, v170
	v_sub_f32_e32 v49, v49, v170
	v_sub_f32_e32 v50, v50, v170
	v_sub_f32_e32 v51, v51, v170
	v_sub_f32_e32 v52, v52, v170
	v_sub_f32_e32 v53, v53, v170
	v_sub_f32_e32 v54, v54, v170
	v_sub_f32_e32 v55, v55, v170
	v_sub_f32_e32 v56, v56, v170
	v_sub_f32_e32 v57, v57, v170
	v_sub_f32_e32 v58, v58, v170
	v_sub_f32_e32 v59, v59, v170
	v_sub_f32_e32 v60, v60, v170
	v_sub_f32_e32 v61, v61, v170
	v_sub_f32_e32 v62, v62, v170
	v_sub_f32_e32 v63, v63, v170
	s_mov_b32 s9, 1
.Lamla_nors_8:
	ds_read_b128 v[136:139], v243 offset:13376
	ds_read_b64_tr_b16 v[192:193], v162 offset:3072
	ds_read_b64_tr_b16 v[194:195], v162 offset:4608
	s_waitcnt lgkmcnt(5)
	v_mfma_f32_32x32x16_bf16 v[80:95], v[140:143], v[112:115], v[218:233]
	v_exp_f32_e32 v32, v32
	v_exp_f32_e32 v48, v48
	ds_read_b128 v[140:143], v243 offset:20032
	ds_read_b64_tr_b16 v[196:197], v162 offset:3136
	ds_read_b64_tr_b16 v[198:199], v162 offset:4672
	v_mfma_f32_32x32x16_bf16 v[0:15], v[184:187], v[104:107], v[0:15]
	v_exp_f32_e32 v33, v33
	v_exp_f32_e32 v49, v49
	ds_read_b64_tr_b16 v[200:201], v162 offset:9216
	ds_read_b64_tr_b16 v[202:203], v162 offset:10752
	s_waitcnt lgkmcnt(9)
	v_mfma_f32_32x32x16_bf16 v[64:79], v[144:147], v[116:119], v[64:79]
	v_exp_f32_e32 v34, v34
	v_exp_f32_e32 v50, v50
	ds_read_b128 v[144:147], v243 offset:13408
	ds_read_b64_tr_b16 v[204:205], v162 offset:9280
	ds_read_b64_tr_b16 v[206:207], v162 offset:10816
	v_mfma_f32_32x32x16_bf16 v[16:31], v[188:191], v[104:107], v[16:31]
	v_cvt_pk_bf16_f32 v96, v32, v33
	v_exp_f32_e32 v35, v35
	s_waitcnt lgkmcnt(11)
	v_mfma_f32_32x32x16_bf16 v[80:95], v[148:151], v[116:119], v[80:95]
	v_exp_f32_e32 v51, v51
	v_exp_f32_e32 v36, v36
	ds_read_b128 v[148:151], v243 offset:20064
	v_mfma_f32_16x16x32_bf16 v[234:237], v[246:249], v[104:107], v[234:237]
	v_cvt_pk_bf16_f32 v104, v48, v49
	v_exp_f32_e32 v52, v52
	v_cvt_pk_bf16_f32 v97, v34, v35
	v_cvt_pk_bf16_f32 v105, v50, v51
	s_waitcnt lgkmcnt(11)
	v_mfma_f32_32x32x16_bf16 v[64:79], v[136:139], v[120:123], v[64:79]
	v_exp_f32_e32 v37, v37
	v_exp_f32_e32 v53, v53
	ds_read_b128 v[136:139], v243 offset:13440
	s_waitcnt lgkmcnt(9)
	v_mfma_f32_32x32x16_bf16 v[80:95], v[140:143], v[120:123], v[80:95]
	v_exp_f32_e32 v38, v38
	v_exp_f32_e32 v54, v54
	ds_read_b128 v[140:143], v243 offset:20096
	v_mfma_f32_32x32x16_bf16 v[0:15], v[192:195], v[100:103], v[0:15]
	v_cvt_pk_bf16_f32 v98, v36, v37
	v_cvt_pk_bf16_f32 v106, v52, v53
	v_exp_f32_e32 v39, v39
	v_exp_f32_e32 v55, v55
	s_waitcnt lgkmcnt(5)
	v_mfma_f32_32x32x16_bf16 v[64:79], v[144:147], v[124:127], v[64:79]
	v_exp_f32_e32 v40, v40
	v_exp_f32_e32 v56, v56
	ds_read_b128 v[144:147], v243 offset:13472
	v_mfma_f32_32x32x16_bf16 v[16:31], v[196:199], v[100:103], v[16:31]
	v_cvt_pk_bf16_f32 v99, v38, v39
	v_cvt_pk_bf16_f32 v107, v54, v55
	v_exp_f32_e32 v41, v41
	s_waitcnt vmcnt(0)
	ds_write_b128 v164, v[156:159]
	s_waitcnt lgkmcnt(4)
	v_mfma_f32_32x32x16_bf16 v[80:95], v[148:151], v[124:127], v[80:95]
	v_exp_f32_e32 v57, v57
	v_exp_f32_e32 v42, v42
	ds_read_b128 v[148:151], v243 offset:20128
	v_mfma_f32_16x16x32_bf16 v[234:237], v[246:249], v[100:103], v[234:237]
	v_exp_f32_e32 v58, v58
	v_cvt_pk_bf16_f32 v100, v40, v41
	s_waitcnt lgkmcnt(4)
	v_mfma_f32_32x32x16_bf16 v[64:79], v[136:139], v[128:131], v[64:79]
	v_exp_f32_e32 v43, v43
	v_exp_f32_e32 v59, v59
	s_waitcnt lgkmcnt(3)
	v_mfma_f32_32x32x16_bf16 v[80:95], v[140:143], v[128:131], v[80:95]
	v_exp_f32_e32 v44, v44
	v_exp_f32_e32 v60, v60
	ds_read_b64_tr_b16 v[176:177], v163 offset:0
	ds_read_b64_tr_b16 v[178:179], v163 offset:1536
	v_mfma_f32_32x32x16_bf16 v[0:15], v[200:203], v[108:111], v[0:15]
	v_cvt_pk_bf16_f32 v101, v42, v43
	v_exp_f32_e32 v45, v45
	v_exp_f32_e32 v61, v61
	ds_read_b64_tr_b16 v[180:181], v163 offset:64
	ds_read_b64_tr_b16 v[182:183], v163 offset:1600
	s_waitcnt lgkmcnt(6)
	v_mfma_f32_32x32x16_bf16 v[64:79], v[144:147], v[132:135], v[64:79]
	v_exp_f32_e32 v46, v46
	v_exp_f32_e32 v62, v62
	ds_read_b64_tr_b16 v[184:185], v163 offset:6144
	ds_read_b64_tr_b16 v[186:187], v163 offset:7680
	v_mfma_f32_32x32x16_bf16 v[16:31], v[204:207], v[108:111], v[16:31]
	v_cvt_pk_bf16_f32 v102, v44, v45
	v_exp_f32_e32 v47, v47
	ds_read_b64_tr_b16 v[188:189], v163 offset:6208
	ds_read_b64_tr_b16 v[190:191], v163 offset:7744
	s_waitcnt lgkmcnt(8)
	v_mfma_f32_32x32x16_bf16 v[80:95], v[148:151], v[132:135], v[80:95]
	v_exp_f32_e32 v63, v63
	v_cvt_pk_bf16_f32 v103, v46, v47
	v_mfma_f32_16x16x32_bf16 v[234:237], v[246:249], v[108:111], v[234:237]
	v_cvt_pk_bf16_f32 v108, v56, v57
	v_cvt_pk_bf16_f32 v109, v58, v59
	v_cvt_pk_bf16_f32 v110, v60, v61
	v_cvt_pk_bf16_f32 v111, v62, v63
	s_cmp_lg_u32 s9, 0
	s_cbranch_scc0 .Lamla_noresc_9
; template <bool MLA>
; DI void attn_phase(const int TID, const int BID, LAS unsigned char* lds, const Params& p, bool need_ctx) {
;     ...
;     for (int item = BID; item < n_items; item += gridDim.x) {
;         int b, head, row0, nk;
;         if (item < 1024) {
;             const int rnd = item >> 8, w = item & 255, xcd = w & 7, slot = w >> 3, qb = slot & 7;
;             if (MLA) { const int grp = (rnd * 8 + xcd) * 4 + (slot >> 3); b = grp >> 4; head = grp & 15; }
;             else { const int grp = rnd * 8 + xcd; b = grp >> 2; head = (grp & 3) * 4 + (slot >> 3); }
;             row0 = b * 2048 + qb * 256; nk = NKEY;
;         }
;         else { const int it = item - 1024; b = it >> 4; head = it & 15; row0 = TL + b * 256; nk = 256; }
	s_nop 15
	v_sub_f32_e32 v218, v218, v170
	v_sub_f32_e32 v219, v219, v170
	v_sub_f32_e32 v220, v220, v170
	v_sub_f32_e32 v221, v221, v170
	v_sub_f32_e32 v222, v222, v170
	v_sub_f32_e32 v223, v223, v170
	v_sub_f32_e32 v224, v224, v170
	v_sub_f32_e32 v225, v225, v170
	v_sub_f32_e32 v226, v226, v170
	v_sub_f32_e32 v227, v227, v170
	v_sub_f32_e32 v228, v228, v170
	v_sub_f32_e32 v229, v229, v170
	v_sub_f32_e32 v230, v230, v170
	v_sub_f32_e32 v231, v231, v170
	v_sub_f32_e32 v232, v232, v170
	v_sub_f32_e32 v233, v233, v170
	v_sub_f32_e32 v64, v64, v170
	v_sub_f32_e32 v65, v65, v170
	v_sub_f32_e32 v66, v66, v170
	v_sub_f32_e32 v67, v67, v170
	v_sub_f32_e32 v68, v68, v170
	v_sub_f32_e32 v69, v69, v170
	v_sub_f32_e32 v70, v70, v170
	v_sub_f32_e32 v71, v71, v170
	v_sub_f32_e32 v72, v72, v170
	v_sub_f32_e32 v73, v73, v170
	v_sub_f32_e32 v74, v74, v170
	v_sub_f32_e32 v75, v75, v170
	v_sub_f32_e32 v76, v76, v170
	v_sub_f32_e32 v77, v77, v170
	v_sub_f32_e32 v78, v78, v170
	v_sub_f32_e32 v79, v79, v170
	v_sub_f32_e32 v80, v80, v170
	v_sub_f32_e32 v81, v81, v170
	v_sub_f32_e32 v82, v82, v170
	v_sub_f32_e32 v83, v83, v170
	v_sub_f32_e32 v84, v84, v170
	v_sub_f32_e32 v85, v85, v170
	v_sub_f32_e32 v86, v86, v170
	v_sub_f32_e32 v87, v87, v170
	v_sub_f32_e32 v88, v88, v170
	v_sub_f32_e32 v89, v89, v170
	v_sub_f32_e32 v90, v90, v170
	v_sub_f32_e32 v91, v91, v170
	v_sub_f32_e32 v92, v92, v170
	v_sub_f32_e32 v93, v93, v170
	v_sub_f32_e32 v94, v94, v170
	v_sub_f32_e32 v95, v95, v170
	v_mul_f32_e32 v0, v0, v166
	v_mul_f32_e32 v1, v1, v166
	v_mul_f32_e32 v2, v2, v166
	v_mul_f32_e32 v3, v3, v166
	v_mul_f32_e32 v4, v4, v166
	v_mul_f32_e32 v5, v5, v166
	v_mul_f32_e32 v6, v6, v166
	v_mul_f32_e32 v7, v7, v166
	v_mul_f32_e32 v8, v8, v166
	v_mul_f32_e32 v9, v9, v166
	v_mul_f32_e32 v10, v10, v166
	v_mul_f32_e32 v11, v11, v166
	v_mul_f32_e32 v12, v12, v166
	v_mul_f32_e32 v13, v13, v166
	v_mul_f32_e32 v14, v14, v166
	v_mul_f32_e32 v15, v15, v166
	v_mul_f32_e32 v16, v16, v166
	v_mul_f32_e32 v17, v17, v166
	v_mul_f32_e32 v18, v18, v166
	v_mul_f32_e32 v19, v19, v166
	v_mul_f32_e32 v20, v20, v166
	v_mul_f32_e32 v21, v21, v166
	v_mul_f32_e32 v22, v22, v166
	v_mul_f32_e32 v23, v23, v166
	v_mul_f32_e32 v24, v24, v166
	v_mul_f32_e32 v25, v25, v166
	v_mul_f32_e32 v26, v26, v166
	v_mul_f32_e32 v27, v27, v166
	v_mul_f32_e32 v28, v28, v166
	v_mul_f32_e32 v29, v29, v166
	v_mul_f32_e32 v30, v30, v166
	v_mul_f32_e32 v31, v31, v166
	v_add_u32_e32 v170, 64, v175
	ds_bpermute_b32 v173, v170, v166
	v_mul_f32_e32 v234, v234, v166
	s_waitcnt lgkmcnt(0)
	v_mul_f32_e32 v235, v235, v173
.Lamla_noresc_9:
	s_nop 4
	s_barrier
	s_add_i32 s59, s6, s31
	s_cmp_ge_i32 s59, s8
	s_cbranch_scc1 .Lamla_nonext
	s_cmpk_gt_i32 s59, 0x3ff
	s_cbranch_scc0 .Lamla_mainitem_next
	s_add_i32 s21, s59, 0xfffffc00
	s_lshr_b32 s15, s21, 4
	s_and_b32 s18, s21, 15
	s_lshl_b32 s20, s15, 8
	s_add_i32 s20, s20, 0x4000
	s_mov_b32 s7, 0
	s_branch .Lamla_decoded_next

; #define AT_STEP(SC0, SC1, SN0, SN1, t, DOK, DOV) do { \
;             if (DOK) AT_GLOADK(((t) + 2) * 64); \
;             if (DOV) { AT_GLOADV(((t) + 1) * 64); AT_QK(SN0, SN1, ((t) + 1) & 1); } \
;             AT_SMPV(SC0, SC1, (t) & 1); \
;             if (DOK) AT_WRITEK((t) & 1); \
;             if (DOV) AT_WRITEV(((t) + 1) & 1); \
;             __syncthreads(); } while (0)
; template <bool MLA>
; DI void attn_phase(const int TID, const int BID, LAS unsigned char* lds, const Params& p, bool need_ctx) {
;     ...
;         AT_STEP(sa0, sa1, sb0, sb1, t, false, true);
;         AT_STEP(sb0, sb1, sa0, sa1, t + 1, false, false);
.Lamla_nonext:
	ds_read_b64_tr_b16 v[192:193], v163 offset:3072
	ds_read_b64_tr_b16 v[194:195], v163 offset:4608
	ds_read_b64_tr_b16 v[196:197], v163 offset:3136
	ds_read_b64_tr_b16 v[198:199], v163 offset:4672
	s_waitcnt lgkmcnt(10)
	v_mfma_f32_32x32x16_bf16 v[0:15], v[176:179], v[96:99], v[0:15]
	v_max3_f32 v168, v64, v65, v66
	v_max3_f32 v170, v80, v81, v82
	v_max3_f32 v168, v168, v67, v68
	v_max3_f32 v170, v170, v83, v84
	v_max3_f32 v168, v168, v69, v70
	v_max3_f32 v170, v170, v85, v86
	v_max3_f32 v168, v168, v71, v72
	v_max3_f32 v170, v170, v87, v88
	v_max3_f32 v168, v168, v73, v74
	s_mov_b32 s55, s52
	s_mov_b32 s52, s53
	s_mov_b32 s53, s54
	s_mov_b32 s54, s55
	s_mov_b32 s9, 0
	ds_read_b64_tr_b16 v[200:201], v163 offset:9216
	ds_read_b64_tr_b16 v[202:203], v163 offset:10752
	ds_read_b64_tr_b16 v[204:205], v163 offset:9280
	ds_read_b64_tr_b16 v[206:207], v163 offset:10816
	s_waitcnt lgkmcnt(12)
	v_mfma_f32_32x32x16_bf16 v[16:31], v[180:183], v[96:99], v[16:31]
	v_max3_f32 v170, v170, v89, v90
	v_max3_f32 v168, v168, v75, v76
	v_max3_f32 v170, v170, v91, v92
	v_max3_f32 v168, v168, v77, v78
	v_max3_f32 v170, v170, v93, v94
	v_max3_f32 v168, v168, v170, v79
	v_max_f32_e32 v168, v168, v95
	v_cmp_lt_f32_e32 vcc, 0x41000000, v168
	s_cbranch_vccz .Lamla_nors_10
	v_mov_b32_e32 v170, v168
	s_nop 1
	v_permlane32_swap_b32_e32 v168, v170
	v_max_f32_e32 v168, v168, v170
	v_max_f32_e32 v170, 0, v168
	v_exp_f32_e64 v166, -v170
	v_sub_f32_e32 v64, v64, v170
	v_sub_f32_e32 v65, v65, v170
	v_sub_f32_e32 v66, v66, v170
	v_sub_f32_e32 v67, v67, v170
	v_sub_f32_e32 v68, v68, v170
	v_sub_f32_e32 v69, v69, v170
	v_sub_f32_e32 v70, v70, v170
	v_sub_f32_e32 v71, v71, v170
	v_sub_f32_e32 v72, v72, v170
	v_sub_f32_e32 v73, v73, v170
	v_sub_f32_e32 v74, v74, v170
	v_sub_f32_e32 v75, v75, v170
	v_sub_f32_e32 v76, v76, v170
	v_sub_f32_e32 v77, v77, v170
	v_sub_f32_e32 v78, v78, v170
	v_sub_f32_e32 v79, v79, v170
	v_sub_f32_e32 v80, v80, v170
	v_sub_f32_e32 v81, v81, v170
	v_sub_f32_e32 v82, v82, v170
	v_sub_f32_e32 v83, v83, v170
	v_sub_f32_e32 v84, v84, v170
	v_sub_f32_e32 v85, v85, v170
	v_sub_f32_e32 v86, v86, v170
	v_sub_f32_e32 v87, v87, v170
	v_sub_f32_e32 v88, v88, v170
	v_sub_f32_e32 v89, v89, v170
	v_sub_f32_e32 v90, v90, v170
	v_sub_f32_e32 v91, v91, v170
	v_sub_f32_e32 v92, v92, v170
	v_sub_f32_e32 v93, v93, v170
	v_sub_f32_e32 v94, v94, v170
	v_sub_f32_e32 v95, v95, v170
	s_mov_b32 s9, 1
.Lamla_nors_10:
	v_add_u32_e32 v162, s53, v240
	v_mfma_f32_16x16x32_bf16 v[234:237], v[246:249], v[96:99], v[234:237]
	v_exp_f32_e32 v64, v64
	v_exp_f32_e32 v80, v80
	v_exp_f32_e32 v65, v65
	v_exp_f32_e32 v81, v81
	s_waitcnt lgkmcnt(10)
	v_mfma_f32_32x32x16_bf16 v[0:15], v[184:187], v[104:107], v[0:15]
	v_exp_f32_e32 v66, v66
	v_exp_f32_e32 v82, v82
	v_cvt_pk_bf16_f32 v96, v64, v65
	v_exp_f32_e32 v67, v67
	s_waitcnt lgkmcnt(8)
	v_mfma_f32_32x32x16_bf16 v[16:31], v[188:191], v[104:107], v[16:31]
	v_exp_f32_e32 v83, v83
	v_exp_f32_e32 v68, v68
	v_exp_f32_e32 v84, v84
	v_cvt_pk_bf16_f32 v97, v66, v67
	v_exp_f32_e32 v69, v69
	v_mfma_f32_16x16x32_bf16 v[234:237], v[246:249], v[104:107], v[234:237]
	v_cvt_pk_bf16_f32 v104, v80, v81
	v_cvt_pk_bf16_f32 v105, v82, v83
	v_exp_f32_e32 v85, v85
	v_exp_f32_e32 v70, v70
	v_exp_f32_e32 v86, v86
	v_cvt_pk_bf16_f32 v98, v68, v69
	s_waitcnt lgkmcnt(6)
	v_mfma_f32_32x32x16_bf16 v[0:15], v[192:195], v[100:103], v[0:15]
	v_cvt_pk_bf16_f32 v106, v84, v85
	v_exp_f32_e32 v71, v71
	v_exp_f32_e32 v87, v87
	v_exp_f32_e32 v72, v72
	v_exp_f32_e32 v88, v88
	ds_read_b64_tr_b16 v[176:177], v162 offset:0
	ds_read_b64_tr_b16 v[178:179], v162 offset:1536
	s_waitcnt lgkmcnt(6)
	v_mfma_f32_32x32x16_bf16 v[16:31], v[196:199], v[100:103], v[16:31]
	v_cvt_pk_bf16_f32 v99, v70, v71
	v_cvt_pk_bf16_f32 v107, v86, v87
	v_exp_f32_e32 v73, v73
	v_exp_f32_e32 v89, v89
	v_exp_f32_e32 v74, v74
	ds_read_b64_tr_b16 v[180:181], v162 offset:64
	ds_read_b64_tr_b16 v[182:183], v162 offset:1600
	v_mfma_f32_16x16x32_bf16 v[234:237], v[246:249], v[100:103], v[234:237]
	v_exp_f32_e32 v90, v90
	v_cvt_pk_bf16_f32 v100, v72, v73
	v_exp_f32_e32 v75, v75
	v_exp_f32_e32 v91, v91
	v_exp_f32_e32 v76, v76
	ds_read_b64_tr_b16 v[184:185], v162 offset:6144
	ds_read_b64_tr_b16 v[186:187], v162 offset:7680
	s_waitcnt lgkmcnt(8)
	v_mfma_f32_32x32x16_bf16 v[0:15], v[200:203], v[108:111], v[0:15]
	v_exp_f32_e32 v92, v92
	v_cvt_pk_bf16_f32 v101, v74, v75
	v_exp_f32_e32 v77, v77
	v_exp_f32_e32 v93, v93
	ds_read_b64_tr_b16 v[188:189], v162 offset:6208
	ds_read_b64_tr_b16 v[190:191], v162 offset:7744
	s_waitcnt lgkmcnt(8)
	v_mfma_f32_32x32x16_bf16 v[16:31], v[204:207], v[108:111], v[16:31]
	v_exp_f32_e32 v78, v78
	v_exp_f32_e32 v94, v94
	v_cvt_pk_bf16_f32 v102, v76, v77
	v_exp_f32_e32 v79, v79
	v_exp_f32_e32 v95, v95
	v_mfma_f32_16x16x32_bf16 v[234:237], v[246:249], v[108:111], v[234:237]
	v_cvt_pk_bf16_f32 v108, v88, v89
	v_cvt_pk_bf16_f32 v109, v90, v91
	v_cvt_pk_bf16_f32 v110, v92, v93
	v_cvt_pk_bf16_f32 v103, v78, v79
	v_cvt_pk_bf16_f32 v111, v94, v95
	s_cmp_lg_u32 s9, 0
	s_cbranch_scc0 .Lamla_noresc_11
	s_nop 15
	v_sub_f32_e32 v218, v218, v170
	v_sub_f32_e32 v219, v219, v170
	v_sub_f32_e32 v220, v220, v170
	v_sub_f32_e32 v221, v221, v170
	v_sub_f32_e32 v222, v222, v170
	v_sub_f32_e32 v223, v223, v170
	v_sub_f32_e32 v224, v224, v170
	v_sub_f32_e32 v225, v225, v170
	v_sub_f32_e32 v226, v226, v170
	v_sub_f32_e32 v227, v227, v170
	v_sub_f32_e32 v228, v228, v170
	v_sub_f32_e32 v229, v229, v170
	v_sub_f32_e32 v230, v230, v170
	v_sub_f32_e32 v231, v231, v170
	v_sub_f32_e32 v232, v232, v170
	v_sub_f32_e32 v233, v233, v170
	v_mul_f32_e32 v0, v0, v166
	v_mul_f32_e32 v1, v1, v166
	v_mul_f32_e32 v2, v2, v166
	v_mul_f32_e32 v3, v3, v166
	v_mul_f32_e32 v4, v4, v166
	v_mul_f32_e32 v5, v5, v166
	v_mul_f32_e32 v6, v6, v166
	v_mul_f32_e32 v7, v7, v166
	v_mul_f32_e32 v8, v8, v166
	v_mul_f32_e32 v9, v9, v166
	v_mul_f32_e32 v10, v10, v166
	v_mul_f32_e32 v11, v11, v166
	v_mul_f32_e32 v12, v12, v166
	v_mul_f32_e32 v13, v13, v166
	v_mul_f32_e32 v14, v14, v166
	v_mul_f32_e32 v15, v15, v166
	v_mul_f32_e32 v16, v16, v166
	v_mul_f32_e32 v17, v17, v166
	v_mul_f32_e32 v18, v18, v166
	v_mul_f32_e32 v19, v19, v166
	v_mul_f32_e32 v20, v20, v166
	v_mul_f32_e32 v21, v21, v166
	v_mul_f32_e32 v22, v22, v166
	v_mul_f32_e32 v23, v23, v166
	v_mul_f32_e32 v24, v24, v166
	v_mul_f32_e32 v25, v25, v166
	v_mul_f32_e32 v26, v26, v166
	v_mul_f32_e32 v27, v27, v166
	v_mul_f32_e32 v28, v28, v166
	v_mul_f32_e32 v29, v29, v166
	v_mul_f32_e32 v30, v30, v166
	v_mul_f32_e32 v31, v31, v166
	v_add_u32_e32 v170, 64, v175
	ds_bpermute_b32 v173, v170, v166
	v_mul_f32_e32 v234, v234, v166
	s_waitcnt lgkmcnt(0)
	v_mul_f32_e32 v235, v235, v173

; #define AT_GLOADK(k0) do { kreg = *(const u32x4*)(Kb + (size_t)((k0) + (tid >> 3)) * 64 + (tid & 7) * 8); \
;             if (MLA) preg = *(const u32x2*)(Pb + (size_t)((k0) + (tid >> 3)) * 32 + (tid & 7) * 4); } while (0)
; #define AT_GLOADV(k0) do { vreg = *(const u32x4*)(Vb + (size_t)((k0) + (tid >> 3)) * 64 + (tid & 7) * 8); } while (0)
; #define AT_WRITEK(buf) do { *(LAS u32x4*)(lds + (buf) * KBUF + (tid >> 3) * KSTR + (tid & 7) * 16) = kreg; \
;             if (MLA) *(LAS u32x2*)(lds + (buf) * KBUF + (tid >> 3) * KSTR + 128 + (tid & 7) * 8) = preg; } while (0)
; #define AT_WRITEV(buf) do { *(LAS u32x4*)(lds + 2 * KBUF + (buf) * VBUF + (tid >> 3) * VSTR + (tid & 7) * 16) = vreg; } while (0)
; #define AT_STEP(SC0, SC1, SN0, SN1, t, DOK, DOV) do { \
;             if (DOK) AT_GLOADK(((t) + 2) * 64); \
;             if (DOV) { AT_GLOADV(((t) + 1) * 64); AT_QK(SN0, SN1, ((t) + 1) & 1); } \
;             AT_SMPV(SC0, SC1, (t) & 1); \
;             if (DOK) AT_WRITEK((t) & 1); \
;             if (DOV) AT_WRITEV(((t) + 1) & 1); \
;             __syncthreads(); } while (0)
; template <bool MLA>
; DI void attn_phase(const int TID, const int BID, LAS unsigned char* lds, const Params& p, bool need_ctx) {
;     ...
;         const int ntile = nk >> 6;
;         AT_GLOADK(0); AT_GLOADV(0); AT_WRITEK(0); AT_WRITEV(0);
;         AT_GLOADK(64); AT_WRITEK(1);
;         __syncthreads();
;         AT_QK(sa0, sa1, 0);
;         __syncthreads();
;         int t = 0;
;         for (; t < ntile - 2; t += 2) {
;             AT_STEP(sa0, sa1, sb0, sb1, t, true, true);
;             AT_STEP(sb0, sb1, sa0, sa1, t + 1, true, true);
;         }
.Lagqa_prio:
	ds_read_b128 v[136:139], v243 offset:0
	ds_read_b128 v[140:143], v243 offset:4608
	ds_read_b128 v[144:147], v243 offset:32
	ds_read_b128 v[148:151], v243 offset:4640
	s_waitcnt lgkmcnt(3)
	v_mfma_f32_32x32x16_bf16 v[32:47], v[136:139], v[112:115], 0
	ds_read_b128 v[136:139], v243 offset:64
	s_waitcnt lgkmcnt(3)
	v_mfma_f32_32x32x16_bf16 v[48:63], v[140:143], v[112:115], 0
	ds_read_b128 v[140:143], v243 offset:4672
	s_waitcnt lgkmcnt(3)
	v_mfma_f32_32x32x16_bf16 v[32:47], v[144:147], v[116:119], v[32:47]
	ds_read_b128 v[144:147], v243 offset:96
	s_waitcnt lgkmcnt(3)
	v_mfma_f32_32x32x16_bf16 v[48:63], v[148:151], v[116:119], v[48:63]
	ds_read_b128 v[148:151], v243 offset:4704
	s_waitcnt lgkmcnt(3)
	v_mfma_f32_32x32x16_bf16 v[32:47], v[136:139], v[120:123], v[32:47]
	s_waitcnt lgkmcnt(2)
	v_mfma_f32_32x32x16_bf16 v[48:63], v[140:143], v[120:123], v[48:63]
	s_waitcnt lgkmcnt(1)
	v_mfma_f32_32x32x16_bf16 v[32:47], v[144:147], v[124:127], v[32:47]
	s_waitcnt lgkmcnt(0)
	v_mfma_f32_32x32x16_bf16 v[48:63], v[148:151], v[124:127], v[48:63]
	s_waitcnt lgkmcnt(0)
	s_nop 7
	s_barrier
	ds_read_b128 v[136:139], v243 offset:9216
	ds_read_b128 v[140:143], v243 offset:13824
	ds_read_b128 v[144:147], v243 offset:9248
	ds_read_b128 v[148:151], v243 offset:13856
	s_waitcnt lgkmcnt(3)
	v_mfma_f32_32x32x16_bf16 v[64:79], v[136:139], v[112:115], v[218:233]
	v_max3_f32 v168, v32, v33, v34
	v_max3_f32 v170, v48, v49, v50
	v_max3_f32 v168, v168, v35, v36
	v_max3_f32 v170, v170, v51, v52
	v_max3_f32 v168, v168, v37, v38
	v_max3_f32 v170, v170, v53, v54
	v_max3_f32 v168, v168, v39, v40
	v_max3_f32 v170, v170, v55, v56
	v_max3_f32 v168, v168, v41, v42
	v_max3_f32 v170, v170, v57, v58
	v_max3_f32 v168, v168, v43, v44
	v_max3_f32 v170, v170, v59, v60
	v_max3_f32 v168, v168, v45, v46
	ds_read_b128 v[136:139], v243 offset:9280
	s_mov_b32 s55, s52
	s_mov_b32 s52, s53
	s_mov_b32 s53, s54
	s_mov_b32 s54, s55
	s_mov_b32 s9, 0
	s_waitcnt lgkmcnt(3)
	v_mfma_f32_32x32x16_bf16 v[80:95], v[140:143], v[112:115], v[218:233]
	v_max3_f32 v170, v170, v61, v62
	v_max3_f32 v168, v168, v170, v47
	v_max_f32_e32 v168, v168, v63
	v_mov_b32_e32 v170, v168
	s_nop 1
	v_permlane32_swap_b32_e32 v168, v170
	v_max_f32_e32 v168, v168, v170
	v_mov_b32_e32 v170, v168
	v_sub_f32_e32 v32, v32, v170
	v_sub_f32_e32 v33, v33, v170
	v_sub_f32_e32 v34, v34, v170
	v_sub_f32_e32 v35, v35, v170
	v_sub_f32_e32 v36, v36, v170
	v_sub_f32_e32 v37, v37, v170
	v_sub_f32_e32 v38, v38, v170
	v_sub_f32_e32 v39, v39, v170
	v_sub_f32_e32 v40, v40, v170
	v_sub_f32_e32 v41, v41, v170
	v_sub_f32_e32 v42, v42, v170
	v_sub_f32_e32 v43, v43, v170
	v_sub_f32_e32 v44, v44, v170
	v_sub_f32_e32 v45, v45, v170
	v_sub_f32_e32 v46, v46, v170
	v_sub_f32_e32 v47, v47, v170
	v_sub_f32_e32 v48, v48, v170
	v_sub_f32_e32 v49, v49, v170
	v_sub_f32_e32 v50, v50, v170
	v_sub_f32_e32 v51, v51, v170
	v_sub_f32_e32 v52, v52, v170
	v_sub_f32_e32 v53, v53, v170
	v_sub_f32_e32 v54, v54, v170
	v_sub_f32_e32 v55, v55, v170
	v_sub_f32_e32 v56, v56, v170
	v_sub_f32_e32 v57, v57, v170
	v_sub_f32_e32 v58, v58, v170
	v_sub_f32_e32 v59, v59, v170
	v_sub_f32_e32 v60, v60, v170
	v_sub_f32_e32 v61, v61, v170
	v_sub_f32_e32 v62, v62, v170
	v_sub_f32_e32 v63, v63, v170
	v_exp_f32_e32 v32, v32
	v_exp_f32_e32 v48, v48
	v_exp_f32_e32 v33, v33
	v_exp_f32_e32 v49, v49
	ds_read_b128 v[140:143], v243 offset:13888
	global_load_dwordx4 v[208:211], v167, s[2:3]
	global_load_dwordx4 v[212:215], v167, s[4:5]
	s_add_u32 s2, s2, 0x2000
	s_addc_u32 s3, s3, 0
	s_add_u32 s4, s4, 0x2000
	s_addc_u32 s5, s5, 0
	v_add_u32_e32 v163, s53, v240
	v_add_u32_e32 v164, s54, v241
	s_waitcnt lgkmcnt(3)
	v_mfma_f32_32x32x16_bf16 v[64:79], v[144:147], v[116:119], v[64:79]
	v_exp_f32_e32 v34, v34
	v_exp_f32_e32 v50, v50
	v_cvt_pk_bf16_f32 v96, v32, v33
	v_cvt_pk_bf16_f32 v104, v48, v49
	v_exp_f32_e32 v35, v35
	v_exp_f32_e32 v51, v51
	v_exp_f32_e32 v36, v36
	ds_read_b128 v[144:147], v243 offset:9312
	ds_read_b64_tr_b16 v[176:177], v163 offset:0
	ds_read_b64_tr_b16 v[178:179], v163 offset:1536
	s_waitcnt lgkmcnt(5)
	v_mfma_f32_32x32x16_bf16 v[80:95], v[148:151], v[116:119], v[80:95]
	v_exp_f32_e32 v52, v52
	v_cvt_pk_bf16_f32 v97, v34, v35
	v_cvt_pk_bf16_f32 v105, v50, v51
	v_exp_f32_e32 v37, v37
	v_exp_f32_e32 v53, v53
	v_exp_f32_e32 v38, v38
	v_exp_f32_e32 v54, v54
	ds_read_b128 v[148:151], v243 offset:13920
	ds_read_b64_tr_b16 v[180:181], v163 offset:64
	ds_read_b64_tr_b16 v[182:183], v163 offset:1600
	s_waitcnt lgkmcnt(7)
	v_mfma_f32_32x32x16_bf16 v[64:79], v[136:139], v[120:123], v[64:79]
	v_cvt_pk_bf16_f32 v98, v36, v37
	v_cvt_pk_bf16_f32 v106, v52, v53
	v_exp_f32_e32 v39, v39
	v_exp_f32_e32 v55, v55
	v_exp_f32_e32 v40, v40
	v_exp_f32_e32 v56, v56
	v_cvt_pk_bf16_f32 v99, v38, v39
	v_cvt_pk_bf16_f32 v107, v54, v55
	ds_read_b64_tr_b16 v[184:185], v163 offset:6144
	ds_read_b64_tr_b16 v[186:187], v163 offset:7680
	s_waitcnt vmcnt(3)
	ds_write_b128 v238, v[152:155]
	s_waitcnt vmcnt(2)
	ds_write_b128 v164, v[156:159]
	s_waitcnt lgkmcnt(10)
	v_mfma_f32_32x32x16_bf16 v[80:95], v[140:143], v[120:123], v[80:95]
	v_exp_f32_e32 v41, v41
	v_exp_f32_e32 v57, v57
	v_exp_f32_e32 v42, v42
	v_exp_f32_e32 v58, v58
	v_cvt_pk_bf16_f32 v100, v40, v41
	v_cvt_pk_bf16_f32 v108, v56, v57
	v_exp_f32_e32 v43, v43
	ds_read_b64_tr_b16 v[188:189], v163 offset:6208
	ds_read_b64_tr_b16 v[190:191], v163 offset:7744
	s_waitcnt lgkmcnt(11)
	v_mfma_f32_32x32x16_bf16 v[64:79], v[144:147], v[124:127], v[64:79]
	v_exp_f32_e32 v59, v59
	v_exp_f32_e32 v44, v44
	v_exp_f32_e32 v60, v60
	v_cvt_pk_bf16_f32 v101, v42, v43
	v_cvt_pk_bf16_f32 v109, v58, v59
	v_exp_f32_e32 v45, v45
	v_exp_f32_e32 v61, v61
	s_waitcnt lgkmcnt(8)
	v_mfma_f32_32x32x16_bf16 v[80:95], v[148:151], v[124:127], v[80:95]
	v_exp_f32_e32 v46, v46
	v_exp_f32_e32 v62, v62
	v_cvt_pk_bf16_f32 v102, v44, v45
	v_cvt_pk_bf16_f32 v110, v60, v61
	v_exp_f32_e32 v47, v47
	v_exp_f32_e32 v63, v63
	v_cvt_pk_bf16_f32 v103, v46, v47
	v_cvt_pk_bf16_f32 v111, v62, v63
	s_nop 15
	v_sub_f32_e32 v218, v218, v170
	v_sub_f32_e32 v219, v219, v170
	v_sub_f32_e32 v220, v220, v170
	v_sub_f32_e32 v221, v221, v170
	v_sub_f32_e32 v222, v222, v170
	v_sub_f32_e32 v223, v223, v170
	v_sub_f32_e32 v224, v224, v170
	v_sub_f32_e32 v225, v225, v170
	v_sub_f32_e32 v226, v226, v170
	v_sub_f32_e32 v227, v227, v170
	v_sub_f32_e32 v228, v228, v170
	v_sub_f32_e32 v229, v229, v170
	v_sub_f32_e32 v230, v230, v170
	v_sub_f32_e32 v231, v231, v170
	v_sub_f32_e32 v232, v232, v170
	v_sub_f32_e32 v233, v233, v170
	v_sub_f32_e32 v64, v64, v170
	v_sub_f32_e32 v65, v65, v170
	v_sub_f32_e32 v66, v66, v170
	v_sub_f32_e32 v67, v67, v170
	v_sub_f32_e32 v68, v68, v170
	v_sub_f32_e32 v69, v69, v170
	v_sub_f32_e32 v70, v70, v170
	v_sub_f32_e32 v71, v71, v170
	v_sub_f32_e32 v72, v72, v170
	v_sub_f32_e32 v73, v73, v170
	v_sub_f32_e32 v74, v74, v170
	v_sub_f32_e32 v75, v75, v170
	v_sub_f32_e32 v76, v76, v170
	v_sub_f32_e32 v77, v77, v170
	v_sub_f32_e32 v78, v78, v170
	v_sub_f32_e32 v79, v79, v170
	v_sub_f32_e32 v80, v80, v170
	v_sub_f32_e32 v81, v81, v170
	v_sub_f32_e32 v82, v82, v170
	v_sub_f32_e32 v83, v83, v170
	v_sub_f32_e32 v84, v84, v170
	v_sub_f32_e32 v85, v85, v170
	v_sub_f32_e32 v86, v86, v170
	v_sub_f32_e32 v87, v87, v170
	v_sub_f32_e32 v88, v88, v170
	v_sub_f32_e32 v89, v89, v170
	v_sub_f32_e32 v90, v90, v170
	v_sub_f32_e32 v91, v91, v170
	v_sub_f32_e32 v92, v92, v170
	v_sub_f32_e32 v93, v93, v170
	v_sub_f32_e32 v94, v94, v170
	v_sub_f32_e32 v95, v95, v170
	s_waitcnt lgkmcnt(2)
	s_waitcnt lgkmcnt(0)
	s_barrier
	s_cmp_eq_u32 s7, 0
	s_cbranch_scc1 .Lagqa_tail
.Lagqa_loop:
	ds_read_b128 v[136:139], v243 offset:0
	ds_read_b128 v[140:143], v243 offset:4608
	ds_read_b128 v[144:147], v243 offset:32
	ds_read_b128 v[148:151], v243 offset:4640
	s_waitcnt lgkmcnt(10)
	v_mfma_f32_32x32x16_bf16 v[0:15], v[176:179], v[96:99], v[0:15]
	v_max3_f32 v168, v64, v65, v66
	v_max3_f32 v170, v80, v81, v82
	v_max3_f32 v168, v168, v67, v68
	v_max3_f32 v170, v170, v83, v84
	v_max3_f32 v168, v168, v69, v70
	s_mov_b32 s55, s52
	s_mov_b32 s52, s53
	s_mov_b32 s53, s54
	s_mov_b32 s54, s55
	s_mov_b32 s9, 0
	s_waitcnt lgkmcnt(8)
	v_mfma_f32_32x32x16_bf16 v[16:31], v[180:183], v[96:99], v[16:31]
	v_max3_f32 v170, v170, v85, v86
	v_max3_f32 v168, v168, v71, v72
	v_max3_f32 v170, v170, v87, v88
	v_max3_f32 v168, v168, v73, v74
	v_max3_f32 v170, v170, v89, v90
	global_load_dwordx4 v[152:155], v167, s[2:3]
	global_load_dwordx4 v[156:159], v167, s[4:5]
	s_add_u32 s2, s2, 0x2000
	s_addc_u32 s3, s3, 0
	s_add_u32 s4, s4, 0x2000
	s_addc_u32 s5, s5, 0
	v_add_u32_e32 v162, s53, v240
	v_add_u32_e32 v164, s54, v241
	v_mfma_f32_16x16x32_bf16 v[234:237], v[246:249], v[96:99], v[234:237]
	v_max3_f32 v168, v168, v75, v76
	v_max3_f32 v170, v170, v91, v92
	v_max3_f32 v168, v168, v77, v78
	v_max3_f32 v170, v170, v93, v94
	v_max3_f32 v168, v168, v170, v79
	s_waitcnt lgkmcnt(3)
	v_mfma_f32_32x32x16_bf16 v[32:47], v[136:139], v[112:115], v[218:233]
	v_max_f32_e32 v168, v168, v95
	v_cmp_lt_f32_e32 vcc, 0x41000000, v168
	s_cbranch_vccz .Lagqa_nors_2
	v_mov_b32_e32 v170, v168
	s_nop 1
	v_permlane32_swap_b32_e32 v168, v170
	v_max_f32_e32 v168, v168, v170
	v_max_f32_e32 v170, 0, v168
	v_exp_f32_e64 v166, -v170
	v_sub_f32_e32 v64, v64, v170
	v_sub_f32_e32 v65, v65, v170
	v_sub_f32_e32 v66, v66, v170
	v_sub_f32_e32 v67, v67, v170
	v_sub_f32_e32 v68, v68, v170
	v_sub_f32_e32 v69, v69, v170
	v_sub_f32_e32 v70, v70, v170
	v_sub_f32_e32 v71, v71, v170
	v_sub_f32_e32 v72, v72, v170
	v_sub_f32_e32 v73, v73, v170
	v_sub_f32_e32 v74, v74, v170
	v_sub_f32_e32 v75, v75, v170
	v_sub_f32_e32 v76, v76, v170
	v_sub_f32_e32 v77, v77, v170
	v_sub_f32_e32 v78, v78, v170
	v_sub_f32_e32 v79, v79, v170
	v_sub_f32_e32 v80, v80, v170
	v_sub_f32_e32 v81, v81, v170
	v_sub_f32_e32 v82, v82, v170
	v_sub_f32_e32 v83, v83, v170
	v_sub_f32_e32 v84, v84, v170
	v_sub_f32_e32 v85, v85, v170
	v_sub_f32_e32 v86, v86, v170
	v_sub_f32_e32 v87, v87, v170
	v_sub_f32_e32 v88, v88, v170
	v_sub_f32_e32 v89, v89, v170
	v_sub_f32_e32 v90, v90, v170
	v_sub_f32_e32 v91, v91, v170
	v_sub_f32_e32 v92, v92, v170
	v_sub_f32_e32 v93, v93, v170
	v_sub_f32_e32 v94, v94, v170
	v_sub_f32_e32 v95, v95, v170
	s_mov_b32 s9, 1
.Lagqa_nors_2:
	v_exp_f32_e32 v64, v64
	ds_read_b128 v[136:139], v243 offset:64
	ds_read_b64_tr_b16 v[192:193], v163 offset:3072
	ds_read_b64_tr_b16 v[194:195], v163 offset:4608
	v_mfma_f32_32x32x16_bf16 v[0:15], v[184:187], v[104:107], v[0:15]
	v_exp_f32_e32 v80, v80
	v_exp_f32_e32 v65, v65
	v_exp_f32_e32 v81, v81
	ds_read_b64_tr_b16 v[196:197], v163 offset:3136
	ds_read_b64_tr_b16 v[198:199], v163 offset:4672
	s_waitcnt lgkmcnt(7)
	v_mfma_f32_32x32x16_bf16 v[48:63], v[140:143], v[112:115], v[218:233]
	v_exp_f32_e32 v66, v66
	v_exp_f32_e32 v82, v82
	ds_read_b128 v[140:143], v243 offset:4672
	ds_read_b64_tr_b16 v[200:201], v163 offset:9216
	ds_read_b64_tr_b16 v[202:203], v163 offset:10752
	v_mfma_f32_32x32x16_bf16 v[16:31], v[188:191], v[104:107], v[16:31]
	v_cvt_pk_bf16_f32 v96, v64, v65
	v_exp_f32_e32 v67, v67
	v_exp_f32_e32 v83, v83
	ds_read_b64_tr_b16 v[204:205], v163 offset:9280
	ds_read_b64_tr_b16 v[206:207], v163 offset:10816
	s_waitcnt lgkmcnt(11)
	v_mfma_f32_32x32x16_bf16 v[32:47], v[144:147], v[116:119], v[32:47]
	v_exp_f32_e32 v68, v68
	v_exp_f32_e32 v84, v84
	v_cvt_pk_bf16_f32 v97, v66, v67
	ds_read_b128 v[144:147], v243 offset:96
	v_mfma_f32_16x16x32_bf16 v[234:237], v[246:249], v[104:107], v[234:237]
	v_cvt_pk_bf16_f32 v104, v80, v81
	v_cvt_pk_bf16_f32 v105, v82, v83
	v_exp_f32_e32 v69, v69
	v_exp_f32_e32 v85, v85
	s_waitcnt lgkmcnt(11)
	v_mfma_f32_32x32x16_bf16 v[48:63], v[148:151], v[116:119], v[48:63]
	v_exp_f32_e32 v70, v70
	v_exp_f32_e32 v86, v86
	v_cvt_pk_bf16_f32 v98, v68, v69
	ds_read_b128 v[148:151], v243 offset:4704
	s_waitcnt lgkmcnt(9)
	v_mfma_f32_32x32x16_bf16 v[0:15], v[192:195], v[100:103], v[0:15]
	v_cvt_pk_bf16_f32 v106, v84, v85
	v_exp_f32_e32 v71, v71
	v_exp_f32_e32 v87, v87
	v_mfma_f32_32x32x16_bf16 v[32:47], v[136:139], v[120:123], v[32:47]
	v_exp_f32_e32 v72, v72
	v_exp_f32_e32 v88, v88
	s_waitcnt vmcnt(3)
	ds_write_b128 v238, v[208:211] offset:9216
	s_waitcnt vmcnt(2)
	ds_write_b128 v164, v[212:215]
	s_waitcnt lgkmcnt(9)
	v_mfma_f32_32x32x16_bf16 v[16:31], v[196:199], v[100:103], v[16:31]
	v_cvt_pk_bf16_f32 v99, v70, v71
	v_cvt_pk_bf16_f32 v107, v86, v87
	v_exp_f32_e32 v73, v73
	v_exp_f32_e32 v89, v89
	s_waitcnt lgkmcnt(8)
	v_mfma_f32_32x32x16_bf16 v[48:63], v[140:143], v[120:123], v[48:63]
	v_exp_f32_e32 v74, v74
	v_exp_f32_e32 v90, v90
	v_mfma_f32_16x16x32_bf16 v[234:237], v[246:249], v[100:103], v[234:237]
	v_cvt_pk_bf16_f32 v100, v72, v73
	v_exp_f32_e32 v75, v75
	v_exp_f32_e32 v91, v91
	ds_read_b64_tr_b16 v[176:177], v162 offset:0
	ds_read_b64_tr_b16 v[178:179], v162 offset:1536
	s_waitcnt lgkmcnt(5)
	v_mfma_f32_32x32x16_bf16 v[32:47], v[144:147], v[124:127], v[32:47]
	v_exp_f32_e32 v76, v76
	v_exp_f32_e32 v92, v92
	v_cvt_pk_bf16_f32 v101, v74, v75
	ds_read_b64_tr_b16 v[180:181], v162 offset:64
	ds_read_b64_tr_b16 v[182:183], v162 offset:1600
	v_mfma_f32_32x32x16_bf16 v[0:15], v[200:203], v[108:111], v[0:15]
	v_exp_f32_e32 v77, v77
	v_exp_f32_e32 v93, v93
	v_exp_f32_e32 v78, v78
	ds_read_b64_tr_b16 v[184:185], v162 offset:6144
	ds_read_b64_tr_b16 v[186:187], v162 offset:7680
	s_waitcnt lgkmcnt(8)
	v_mfma_f32_32x32x16_bf16 v[48:63], v[148:151], v[124:127], v[48:63]
	v_exp_f32_e32 v94, v94
	v_cvt_pk_bf16_f32 v102, v76, v77
	v_exp_f32_e32 v79, v79
	ds_read_b64_tr_b16 v[188:189], v162 offset:6208
	ds_read_b64_tr_b16 v[190:191], v162 offset:7744
	v_mfma_f32_32x32x16_bf16 v[16:31], v[204:207], v[108:111], v[16:31]
	v_exp_f32_e32 v95, v95
	v_cvt_pk_bf16_f32 v103, v78, v79
	v_mfma_f32_16x16x32_bf16 v[234:237], v[246:249], v[108:111], v[234:237]
	v_cvt_pk_bf16_f32 v108, v88, v89
	v_cvt_pk_bf16_f32 v109, v90, v91
	v_cvt_pk_bf16_f32 v110, v92, v93
	v_cvt_pk_bf16_f32 v111, v94, v95
	s_cmp_lg_u32 s9, 0
	s_cbranch_scc0 .Lagqa_noresc_3
	s_nop 15
	v_sub_f32_e32 v218, v218, v170
	v_sub_f32_e32 v219, v219, v170
	v_sub_f32_e32 v220, v220, v170
	v_sub_f32_e32 v221, v221, v170
	v_sub_f32_e32 v222, v222, v170
	v_sub_f32_e32 v223, v223, v170
	v_sub_f32_e32 v224, v224, v170
	v_sub_f32_e32 v225, v225, v170
	v_sub_f32_e32 v226, v226, v170
	v_sub_f32_e32 v227, v227, v170
	v_sub_f32_e32 v228, v228, v170
	v_sub_f32_e32 v229, v229, v170
	v_sub_f32_e32 v230, v230, v170
	v_sub_f32_e32 v231, v231, v170
	v_sub_f32_e32 v232, v232, v170
	v_sub_f32_e32 v233, v233, v170
	v_sub_f32_e32 v32, v32, v170
	v_sub_f32_e32 v33, v33, v170
	v_sub_f32_e32 v34, v34, v170
	v_sub_f32_e32 v35, v35, v170
	v_sub_f32_e32 v36, v36, v170
	v_sub_f32_e32 v37, v37, v170
	v_sub_f32_e32 v38, v38, v170
	v_sub_f32_e32 v39, v39, v170
	v_sub_f32_e32 v40, v40, v170
	v_sub_f32_e32 v41, v41, v170
	v_sub_f32_e32 v42, v42, v170
	v_sub_f32_e32 v43, v43, v170
	v_sub_f32_e32 v44, v44, v170
	v_sub_f32_e32 v45, v45, v170
	v_sub_f32_e32 v46, v46, v170
	v_sub_f32_e32 v47, v47, v170
	v_sub_f32_e32 v48, v48, v170
	v_sub_f32_e32 v49, v49, v170
	v_sub_f32_e32 v50, v50, v170
	v_sub_f32_e32 v51, v51, v170
	v_sub_f32_e32 v52, v52, v170
	v_sub_f32_e32 v53, v53, v170
	v_sub_f32_e32 v54, v54, v170
	v_sub_f32_e32 v55, v55, v170
	v_sub_f32_e32 v56, v56, v170
	v_sub_f32_e32 v57, v57, v170
	v_sub_f32_e32 v58, v58, v170
	v_sub_f32_e32 v59, v59, v170
	v_sub_f32_e32 v60, v60, v170
	v_sub_f32_e32 v61, v61, v170
	v_sub_f32_e32 v62, v62, v170
	v_sub_f32_e32 v63, v63, v170
	v_mul_f32_e32 v0, v0, v166
	v_mul_f32_e32 v1, v1, v166
	v_mul_f32_e32 v2, v2, v166
	v_mul_f32_e32 v3, v3, v166
	v_mul_f32_e32 v4, v4, v166
	v_mul_f32_e32 v5, v5, v166
	v_mul_f32_e32 v6, v6, v166
	v_mul_f32_e32 v7, v7, v166
	v_mul_f32_e32 v8, v8, v166
	v_mul_f32_e32 v9, v9, v166
	v_mul_f32_e32 v10, v10, v166
	v_mul_f32_e32 v11, v11, v166
	v_mul_f32_e32 v12, v12, v166
	v_mul_f32_e32 v13, v13, v166
	v_mul_f32_e32 v14, v14, v166
	v_mul_f32_e32 v15, v15, v166
	v_mul_f32_e32 v16, v16, v166
	v_mul_f32_e32 v17, v17, v166
	v_mul_f32_e32 v18, v18, v166
	v_mul_f32_e32 v19, v19, v166
	v_mul_f32_e32 v20, v20, v166
	v_mul_f32_e32 v21, v21, v166
	v_mul_f32_e32 v22, v22, v166
	v_mul_f32_e32 v23, v23, v166
	v_mul_f32_e32 v24, v24, v166
	v_mul_f32_e32 v25, v25, v166
	v_mul_f32_e32 v26, v26, v166
	v_mul_f32_e32 v27, v27, v166
	v_mul_f32_e32 v28, v28, v166
	v_mul_f32_e32 v29, v29, v166
	v_mul_f32_e32 v30, v30, v166
	v_mul_f32_e32 v31, v31, v166
	v_add_u32_e32 v170, 64, v175
	ds_bpermute_b32 v173, v170, v166
	v_mul_f32_e32 v234, v234, v166
	s_waitcnt lgkmcnt(0)
	v_mul_f32_e32 v235, v235, v173
.Lagqa_noresc_3:
	s_waitcnt lgkmcnt(8)
	s_barrier
	ds_read_b128 v[136:139], v243 offset:9216
	ds_read_b128 v[140:143], v243 offset:13824
	ds_read_b128 v[144:147], v243 offset:9248
	ds_read_b128 v[148:151], v243 offset:13856
	s_waitcnt lgkmcnt(10)
	v_mfma_f32_32x32x16_bf16 v[0:15], v[176:179], v[96:99], v[0:15]
	v_max3_f32 v168, v32, v33, v34
	v_max3_f32 v170, v48, v49, v50
	v_max3_f32 v168, v168, v35, v36
	v_max3_f32 v170, v170, v51, v52
	v_max3_f32 v168, v168, v37, v38
	s_mov_b32 s55, s52
	s_mov_b32 s52, s53
	s_mov_b32 s53, s54
	s_mov_b32 s54, s55
	s_mov_b32 s9, 0
	s_waitcnt lgkmcnt(8)
	v_mfma_f32_32x32x16_bf16 v[16:31], v[180:183], v[96:99], v[16:31]
	v_max3_f32 v170, v170, v53, v54
	v_max3_f32 v168, v168, v39, v40
	v_max3_f32 v170, v170, v55, v56
	v_max3_f32 v168, v168, v41, v42
	v_max3_f32 v170, v170, v57, v58
	global_load_dwordx4 v[208:211], v167, s[2:3]
	global_load_dwordx4 v[212:215], v167, s[4:5]
	s_add_u32 s2, s2, 0x2000
	s_addc_u32 s3, s3, 0
	s_add_u32 s4, s4, 0x2000
	s_addc_u32 s5, s5, 0
	v_add_u32_e32 v163, s53, v240
	v_add_u32_e32 v164, s54, v241
	v_mfma_f32_16x16x32_bf16 v[234:237], v[246:249], v[96:99], v[234:237]
	v_max3_f32 v168, v168, v43, v44
	v_max3_f32 v170, v170, v59, v60
	v_max3_f32 v168, v168, v45, v46
	v_max3_f32 v170, v170, v61, v62
	v_max3_f32 v168, v168, v170, v47
	s_waitcnt lgkmcnt(3)
	v_mfma_f32_32x32x16_bf16 v[64:79], v[136:139], v[112:115], v[218:233]
	v_max_f32_e32 v168, v168, v63
	v_cmp_lt_f32_e32 vcc, 0x41000000, v168
	s_cbranch_vccz .Lagqa_nors_4
	v_mov_b32_e32 v170, v168
	s_nop 1
	v_permlane32_swap_b32_e32 v168, v170
	v_max_f32_e32 v168, v168, v170
	v_max_f32_e32 v170, 0, v168
	v_exp_f32_e64 v166, -v170
	v_sub_f32_e32 v32, v32, v170
	v_sub_f32_e32 v33, v33, v170
	v_sub_f32_e32 v34, v34, v170
	v_sub_f32_e32 v35, v35, v170
	v_sub_f32_e32 v36, v36, v170
	v_sub_f32_e32 v37, v37, v170
	v_sub_f32_e32 v38, v38, v170
	v_sub_f32_e32 v39, v39, v170
	v_sub_f32_e32 v40, v40, v170
	v_sub_f32_e32 v41, v41, v170
	v_sub_f32_e32 v42, v42, v170
	v_sub_f32_e32 v43, v43, v170
	v_sub_f32_e32 v44, v44, v170
	v_sub_f32_e32 v45, v45, v170
	v_sub_f32_e32 v46, v46, v170
	v_sub_f32_e32 v47, v47, v170
	v_sub_f32_e32 v48, v48, v170
	v_sub_f32_e32 v49, v49, v170
	v_sub_f32_e32 v50, v50, v170
	v_sub_f32_e32 v51, v51, v170
	v_sub_f32_e32 v52, v52, v170
	v_sub_f32_e32 v53, v53, v170
	v_sub_f32_e32 v54, v54, v170
	v_sub_f32_e32 v55, v55, v170
	v_sub_f32_e32 v56, v56, v170
	v_sub_f32_e32 v57, v57, v170
	v_sub_f32_e32 v58, v58, v170
	v_sub_f32_e32 v59, v59, v170
	v_sub_f32_e32 v60, v60, v170
	v_sub_f32_e32 v61, v61, v170
	v_sub_f32_e32 v62, v62, v170
	v_sub_f32_e32 v63, v63, v170
	s_mov_b32 s9, 1
.Lagqa_nors_4:
	v_exp_f32_e32 v32, v32
	ds_read_b128 v[136:139], v243 offset:9280
	ds_read_b64_tr_b16 v[192:193], v162 offset:3072
	ds_read_b64_tr_b16 v[194:195], v162 offset:4608
	v_mfma_f32_32x32x16_bf16 v[0:15], v[184:187], v[104:107], v[0:15]
	v_exp_f32_e32 v48, v48
	v_exp_f32_e32 v33, v33
	v_exp_f32_e32 v49, v49
	ds_read_b64_tr_b16 v[196:197], v162 offset:3136
	ds_read_b64_tr_b16 v[198:199], v162 offset:4672
	s_waitcnt lgkmcnt(7)
	v_mfma_f32_32x32x16_bf16 v[80:95], v[140:143], v[112:115], v[218:233]
	v_exp_f32_e32 v34, v34
	v_exp_f32_e32 v50, v50
	ds_read_b128 v[140:143], v243 offset:13888
	ds_read_b64_tr_b16 v[200:201], v162 offset:9216
	ds_read_b64_tr_b16 v[202:203], v162 offset:10752
	v_mfma_f32_32x32x16_bf16 v[16:31], v[188:191], v[104:107], v[16:31]
	v_cvt_pk_bf16_f32 v96, v32, v33
	v_exp_f32_e32 v35, v35
	v_exp_f32_e32 v51, v51
	ds_read_b64_tr_b16 v[204:205], v162 offset:9280
	ds_read_b64_tr_b16 v[206:207], v162 offset:10816
	s_waitcnt lgkmcnt(11)
	v_mfma_f32_32x32x16_bf16 v[64:79], v[144:147], v[116:119], v[64:79]
	v_exp_f32_e32 v36, v36
	v_exp_f32_e32 v52, v52
	v_cvt_pk_bf16_f32 v97, v34, v35
	ds_read_b128 v[144:147], v243 offset:9312
	v_mfma_f32_16x16x32_bf16 v[234:237], v[246:249], v[104:107], v[234:237]
	v_cvt_pk_bf16_f32 v104, v48, v49
	v_cvt_pk_bf16_f32 v105, v50, v51
	v_exp_f32_e32 v37, v37
	v_exp_f32_e32 v53, v53
	s_waitcnt lgkmcnt(11)
	v_mfma_f32_32x32x16_bf16 v[80:95], v[148:151], v[116:119], v[80:95]
	v_exp_f32_e32 v38, v38
	v_exp_f32_e32 v54, v54
	v_cvt_pk_bf16_f32 v98, v36, v37
	ds_read_b128 v[148:151], v243 offset:13920
	s_waitcnt lgkmcnt(9)
	v_mfma_f32_32x32x16_bf16 v[0:15], v[192:195], v[100:103], v[0:15]
	v_cvt_pk_bf16_f32 v106, v52, v53
	v_exp_f32_e32 v39, v39
	v_exp_f32_e32 v55, v55
	v_mfma_f32_32x32x16_bf16 v[64:79], v[136:139], v[120:123], v[64:79]
	v_exp_f32_e32 v40, v40
	v_exp_f32_e32 v56, v56
	s_waitcnt vmcnt(3)
	ds_write_b128 v238, v[152:155]
	s_waitcnt vmcnt(2)
	ds_write_b128 v164, v[156:159]
	s_waitcnt lgkmcnt(9)
	v_mfma_f32_32x32x16_bf16 v[16:31], v[196:199], v[100:103], v[16:31]
	v_cvt_pk_bf16_f32 v99, v38, v39
	v_cvt_pk_bf16_f32 v107, v54, v55
	v_exp_f32_e32 v41, v41
	v_exp_f32_e32 v57, v57
	s_waitcnt lgkmcnt(8)
	v_mfma_f32_32x32x16_bf16 v[80:95], v[140:143], v[120:123], v[80:95]
	v_exp_f32_e32 v42, v42
	v_exp_f32_e32 v58, v58
	v_mfma_f32_16x16x32_bf16 v[234:237], v[246:249], v[100:103], v[234:237]
	v_cvt_pk_bf16_f32 v100, v40, v41
	v_exp_f32_e32 v43, v43
	v_exp_f32_e32 v59, v59
	ds_read_b64_tr_b16 v[176:177], v163 offset:0
	ds_read_b64_tr_b16 v[178:179], v163 offset:1536
	s_waitcnt lgkmcnt(5)
	v_mfma_f32_32x32x16_bf16 v[64:79], v[144:147], v[124:127], v[64:79]
	v_exp_f32_e32 v44, v44
	v_exp_f32_e32 v60, v60
	v_cvt_pk_bf16_f32 v101, v42, v43
	ds_read_b64_tr_b16 v[180:181], v163 offset:64
	ds_read_b64_tr_b16 v[182:183], v163 offset:1600
	v_mfma_f32_32x32x16_bf16 v[0:15], v[200:203], v[108:111], v[0:15]
	v_exp_f32_e32 v45, v45
	v_exp_f32_e32 v61, v61
	v_exp_f32_e32 v46, v46
	ds_read_b64_tr_b16 v[184:185], v163 offset:6144
	ds_read_b64_tr_b16 v[186:187], v163 offset:7680
	s_waitcnt lgkmcnt(8)
	v_mfma_f32_32x32x16_bf16 v[80:95], v[148:151], v[124:127], v[80:95]
	v_exp_f32_e32 v62, v62
	v_cvt_pk_bf16_f32 v102, v44, v45
	v_exp_f32_e32 v47, v47
	ds_read_b64_tr_b16 v[188:189], v163 offset:6208
	ds_read_b64_tr_b16 v[190:191], v163 offset:7744
	v_mfma_f32_32x32x16_bf16 v[16:31], v[204:207], v[108:111], v[16:31]
	v_exp_f32_e32 v63, v63
	v_cvt_pk_bf16_f32 v103, v46, v47
	v_mfma_f32_16x16x32_bf16 v[234:237], v[246:249], v[108:111], v[234:237]
	v_cvt_pk_bf16_f32 v108, v56, v57
	v_cvt_pk_bf16_f32 v109, v58, v59
	v_cvt_pk_bf16_f32 v110, v60, v61
	v_cvt_pk_bf16_f32 v111, v62, v63
	s_cmp_lg_u32 s9, 0
	s_cbranch_scc0 .Lagqa_noresc_5
	s_nop 15
	v_sub_f32_e32 v218, v218, v170
	v_sub_f32_e32 v219, v219, v170
	v_sub_f32_e32 v220, v220, v170
	v_sub_f32_e32 v221, v221, v170
	v_sub_f32_e32 v222, v222, v170
	v_sub_f32_e32 v223, v223, v170
	v_sub_f32_e32 v224, v224, v170
	v_sub_f32_e32 v225, v225, v170
	v_sub_f32_e32 v226, v226, v170
	v_sub_f32_e32 v227, v227, v170
	v_sub_f32_e32 v228, v228, v170
	v_sub_f32_e32 v229, v229, v170
	v_sub_f32_e32 v230, v230, v170
	v_sub_f32_e32 v231, v231, v170
	v_sub_f32_e32 v232, v232, v170
	v_sub_f32_e32 v233, v233, v170
	v_sub_f32_e32 v64, v64, v170
	v_sub_f32_e32 v65, v65, v170
	v_sub_f32_e32 v66, v66, v170
	v_sub_f32_e32 v67, v67, v170
	v_sub_f32_e32 v68, v68, v170
	v_sub_f32_e32 v69, v69, v170
	v_sub_f32_e32 v70, v70, v170
	v_sub_f32_e32 v71, v71, v170
	v_sub_f32_e32 v72, v72, v170
	v_sub_f32_e32 v73, v73, v170
	v_sub_f32_e32 v74, v74, v170
	v_sub_f32_e32 v75, v75, v170
	v_sub_f32_e32 v76, v76, v170
	v_sub_f32_e32 v77, v77, v170
	v_sub_f32_e32 v78, v78, v170
	v_sub_f32_e32 v79, v79, v170
	v_sub_f32_e32 v80, v80, v170
	v_sub_f32_e32 v81, v81, v170
	v_sub_f32_e32 v82, v82, v170
	v_sub_f32_e32 v83, v83, v170
	v_sub_f32_e32 v84, v84, v170
	v_sub_f32_e32 v85, v85, v170
	v_sub_f32_e32 v86, v86, v170
	v_sub_f32_e32 v87, v87, v170
	v_sub_f32_e32 v88, v88, v170
	v_sub_f32_e32 v89, v89, v170
	v_sub_f32_e32 v90, v90, v170
	v_sub_f32_e32 v91, v91, v170
	v_sub_f32_e32 v92, v92, v170
	v_sub_f32_e32 v93, v93, v170
	v_sub_f32_e32 v94, v94, v170
	v_sub_f32_e32 v95, v95, v170
	v_mul_f32_e32 v0, v0, v166
	v_mul_f32_e32 v1, v1, v166
	v_mul_f32_e32 v2, v2, v166
	v_mul_f32_e32 v3, v3, v166
	v_mul_f32_e32 v4, v4, v166
	v_mul_f32_e32 v5, v5, v166
	v_mul_f32_e32 v6, v6, v166
	v_mul_f32_e32 v7, v7, v166
	v_mul_f32_e32 v8, v8, v166
	v_mul_f32_e32 v9, v9, v166
	v_mul_f32_e32 v10, v10, v166
	v_mul_f32_e32 v11, v11, v166
	v_mul_f32_e32 v12, v12, v166
	v_mul_f32_e32 v13, v13, v166
	v_mul_f32_e32 v14, v14, v166
	v_mul_f32_e32 v15, v15, v166
	v_mul_f32_e32 v16, v16, v166
	v_mul_f32_e32 v17, v17, v166
	v_mul_f32_e32 v18, v18, v166
	v_mul_f32_e32 v19, v19, v166
	v_mul_f32_e32 v20, v20, v166
	v_mul_f32_e32 v21, v21, v166
	v_mul_f32_e32 v22, v22, v166
	v_mul_f32_e32 v23, v23, v166
	v_mul_f32_e32 v24, v24, v166
	v_mul_f32_e32 v25, v25, v166
	v_mul_f32_e32 v26, v26, v166
	v_mul_f32_e32 v27, v27, v166
	v_mul_f32_e32 v28, v28, v166
	v_mul_f32_e32 v29, v29, v166
	v_mul_f32_e32 v30, v30, v166
	v_mul_f32_e32 v31, v31, v166
	v_add_u32_e32 v170, 64, v175
	ds_bpermute_b32 v173, v170, v166
	v_mul_f32_e32 v234, v234, v166
	s_waitcnt lgkmcnt(0)
	v_mul_f32_e32 v235, v235, v173

; #define AT_STEP(SC0, SC1, SN0, SN1, t, DOK, DOV) do { \
;             if (DOK) AT_GLOADK(((t) + 2) * 64); \
;             if (DOV) { AT_GLOADV(((t) + 1) * 64); AT_QK(SN0, SN1, ((t) + 1) & 1); } \
;             AT_SMPV(SC0, SC1, (t) & 1); \
;             if (DOK) AT_WRITEK((t) & 1); \
;             if (DOV) AT_WRITEV(((t) + 1) & 1); \
;             __syncthreads(); } while (0)
; template <bool MLA>
; DI void attn_phase(const int TID, const int BID, LAS unsigned char* lds, const Params& p, bool need_ctx) {
;     ...
;         AT_STEP(sa0, sa1, sb0, sb1, t, false, true);
.Lagqa_tail:
	ds_read_b128 v[136:139], v243 offset:0
	ds_read_b128 v[140:143], v243 offset:4608
	ds_read_b128 v[144:147], v243 offset:32
	ds_read_b128 v[148:151], v243 offset:4640
	s_waitcnt lgkmcnt(10)
	v_mfma_f32_32x32x16_bf16 v[0:15], v[176:179], v[96:99], v[0:15]
	v_max3_f32 v168, v64, v65, v66
	v_max3_f32 v170, v80, v81, v82
	v_max3_f32 v168, v168, v67, v68
	v_max3_f32 v170, v170, v83, v84
	v_max3_f32 v168, v168, v69, v70
	s_mov_b32 s55, s52
	s_mov_b32 s52, s53
	s_mov_b32 s53, s54
	s_mov_b32 s54, s55
	s_mov_b32 s9, 0
	s_waitcnt lgkmcnt(8)
	v_mfma_f32_32x32x16_bf16 v[16:31], v[180:183], v[96:99], v[16:31]
	v_max3_f32 v170, v170, v85, v86
	v_max3_f32 v168, v168, v71, v72
	v_max3_f32 v170, v170, v87, v88
	v_max3_f32 v168, v168, v73, v74
	v_max3_f32 v170, v170, v89, v90
	global_load_dwordx4 v[156:159], v167, s[4:5]
	s_add_u32 s4, s4, 0x2000
	s_addc_u32 s5, s5, 0
	v_add_u32_e32 v162, s53, v240
	v_add_u32_e32 v164, s54, v241
	v_mfma_f32_16x16x32_bf16 v[234:237], v[246:249], v[96:99], v[234:237]
	v_max3_f32 v168, v168, v75, v76
	v_max3_f32 v170, v170, v91, v92
	v_max3_f32 v168, v168, v77, v78
	v_max3_f32 v170, v170, v93, v94
	v_max3_f32 v168, v168, v170, v79
	s_waitcnt lgkmcnt(3)
	v_mfma_f32_32x32x16_bf16 v[32:47], v[136:139], v[112:115], v[218:233]
	v_max_f32_e32 v168, v168, v95
	v_cmp_lt_f32_e32 vcc, 0x41000000, v168
	s_cbranch_vccz .Lagqa_nors_6
	v_mov_b32_e32 v170, v168
	s_nop 1
	v_permlane32_swap_b32_e32 v168, v170
	v_max_f32_e32 v168, v168, v170
	v_max_f32_e32 v170, 0, v168
	v_exp_f32_e64 v166, -v170
	v_sub_f32_e32 v64, v64, v170
	v_sub_f32_e32 v65, v65, v170
	v_sub_f32_e32 v66, v66, v170
	v_sub_f32_e32 v67, v67, v170
	v_sub_f32_e32 v68, v68, v170
	v_sub_f32_e32 v69, v69, v170
	v_sub_f32_e32 v70, v70, v170
	v_sub_f32_e32 v71, v71, v170
	v_sub_f32_e32 v72, v72, v170
	v_sub_f32_e32 v73, v73, v170
	v_sub_f32_e32 v74, v74, v170
	v_sub_f32_e32 v75, v75, v170
	v_sub_f32_e32 v76, v76, v170
	v_sub_f32_e32 v77, v77, v170
	v_sub_f32_e32 v78, v78, v170
	v_sub_f32_e32 v79, v79, v170
	v_sub_f32_e32 v80, v80, v170
	v_sub_f32_e32 v81, v81, v170
	v_sub_f32_e32 v82, v82, v170
	v_sub_f32_e32 v83, v83, v170
	v_sub_f32_e32 v84, v84, v170
	v_sub_f32_e32 v85, v85, v170
	v_sub_f32_e32 v86, v86, v170
	v_sub_f32_e32 v87, v87, v170
	v_sub_f32_e32 v88, v88, v170
	v_sub_f32_e32 v89, v89, v170
	v_sub_f32_e32 v90, v90, v170
	v_sub_f32_e32 v91, v91, v170
	v_sub_f32_e32 v92, v92, v170
	v_sub_f32_e32 v93, v93, v170
	v_sub_f32_e32 v94, v94, v170
	v_sub_f32_e32 v95, v95, v170
	s_mov_b32 s9, 1
.Lagqa_nors_6:
	v_exp_f32_e32 v64, v64
	ds_read_b128 v[136:139], v243 offset:64
	ds_read_b64_tr_b16 v[192:193], v163 offset:3072
	ds_read_b64_tr_b16 v[194:195], v163 offset:4608
	v_mfma_f32_32x32x16_bf16 v[0:15], v[184:187], v[104:107], v[0:15]
	v_exp_f32_e32 v80, v80
	v_exp_f32_e32 v65, v65
	v_exp_f32_e32 v81, v81
	ds_read_b64_tr_b16 v[196:197], v163 offset:3136
	ds_read_b64_tr_b16 v[198:199], v163 offset:4672
	s_waitcnt lgkmcnt(7)
	v_mfma_f32_32x32x16_bf16 v[48:63], v[140:143], v[112:115], v[218:233]
	v_exp_f32_e32 v66, v66
	v_exp_f32_e32 v82, v82
	ds_read_b128 v[140:143], v243 offset:4672
	ds_read_b64_tr_b16 v[200:201], v163 offset:9216
	ds_read_b64_tr_b16 v[202:203], v163 offset:10752
	v_mfma_f32_32x32x16_bf16 v[16:31], v[188:191], v[104:107], v[16:31]
	v_cvt_pk_bf16_f32 v96, v64, v65
	v_exp_f32_e32 v67, v67
	v_exp_f32_e32 v83, v83
	ds_read_b64_tr_b16 v[204:205], v163 offset:9280
	ds_read_b64_tr_b16 v[206:207], v163 offset:10816
	s_waitcnt lgkmcnt(11)
	v_mfma_f32_32x32x16_bf16 v[32:47], v[144:147], v[116:119], v[32:47]
	v_exp_f32_e32 v68, v68
	v_exp_f32_e32 v84, v84
	v_cvt_pk_bf16_f32 v97, v66, v67
	ds_read_b128 v[144:147], v243 offset:96
	v_mfma_f32_16x16x32_bf16 v[234:237], v[246:249], v[104:107], v[234:237]
	v_cvt_pk_bf16_f32 v104, v80, v81
	v_cvt_pk_bf16_f32 v105, v82, v83
	v_exp_f32_e32 v69, v69
	v_exp_f32_e32 v85, v85
	s_waitcnt lgkmcnt(11)
	v_mfma_f32_32x32x16_bf16 v[48:63], v[148:151], v[116:119], v[48:63]
	v_exp_f32_e32 v70, v70
	v_exp_f32_e32 v86, v86
	v_cvt_pk_bf16_f32 v98, v68, v69
	ds_read_b128 v[148:151], v243 offset:4704
	s_waitcnt lgkmcnt(9)
	v_mfma_f32_32x32x16_bf16 v[0:15], v[192:195], v[100:103], v[0:15]
	v_cvt_pk_bf16_f32 v106, v84, v85
	v_exp_f32_e32 v71, v71
	v_exp_f32_e32 v87, v87
	v_mfma_f32_32x32x16_bf16 v[32:47], v[136:139], v[120:123], v[32:47]
	v_exp_f32_e32 v72, v72
	v_exp_f32_e32 v88, v88
	s_waitcnt vmcnt(2)
	ds_write_b128 v238, v[208:211] offset:9216
	s_waitcnt vmcnt(1)
	ds_write_b128 v164, v[212:215]
	s_waitcnt lgkmcnt(9)
	v_mfma_f32_32x32x16_bf16 v[16:31], v[196:199], v[100:103], v[16:31]
	v_cvt_pk_bf16_f32 v99, v70, v71
	v_cvt_pk_bf16_f32 v107, v86, v87
	v_exp_f32_e32 v73, v73
	v_exp_f32_e32 v89, v89
	s_waitcnt lgkmcnt(8)
	v_mfma_f32_32x32x16_bf16 v[48:63], v[140:143], v[120:123], v[48:63]
	v_exp_f32_e32 v74, v74
	v_exp_f32_e32 v90, v90
	v_mfma_f32_16x16x32_bf16 v[234:237], v[246:249], v[100:103], v[234:237]
	v_cvt_pk_bf16_f32 v100, v72, v73
	v_exp_f32_e32 v75, v75
	v_exp_f32_e32 v91, v91
	ds_read_b64_tr_b16 v[176:177], v162 offset:0
	ds_read_b64_tr_b16 v[178:179], v162 offset:1536
	s_waitcnt lgkmcnt(5)
	v_mfma_f32_32x32x16_bf16 v[32:47], v[144:147], v[124:127], v[32:47]
	v_exp_f32_e32 v76, v76
	v_exp_f32_e32 v92, v92
	v_cvt_pk_bf16_f32 v101, v74, v75
	ds_read_b64_tr_b16 v[180:181], v162 offset:64
	ds_read_b64_tr_b16 v[182:183], v162 offset:1600
	v_mfma_f32_32x32x16_bf16 v[0:15], v[200:203], v[108:111], v[0:15]
	v_exp_f32_e32 v77, v77
	v_exp_f32_e32 v93, v93
	v_exp_f32_e32 v78, v78
	ds_read_b64_tr_b16 v[184:185], v162 offset:6144
	ds_read_b64_tr_b16 v[186:187], v162 offset:7680
	s_waitcnt lgkmcnt(8)
	v_mfma_f32_32x32x16_bf16 v[48:63], v[148:151], v[124:127], v[48:63]
	v_exp_f32_e32 v94, v94
	v_cvt_pk_bf16_f32 v102, v76, v77
	v_exp_f32_e32 v79, v79
	ds_read_b64_tr_b16 v[188:189], v162 offset:6208
	ds_read_b64_tr_b16 v[190:191], v162 offset:7744
	v_mfma_f32_32x32x16_bf16 v[16:31], v[204:207], v[108:111], v[16:31]
	v_exp_f32_e32 v95, v95
	v_cvt_pk_bf16_f32 v103, v78, v79
	v_mfma_f32_16x16x32_bf16 v[234:237], v[246:249], v[108:111], v[234:237]
	v_cvt_pk_bf16_f32 v108, v88, v89
	v_cvt_pk_bf16_f32 v109, v90, v91
	v_cvt_pk_bf16_f32 v110, v92, v93
	v_cvt_pk_bf16_f32 v111, v94, v95
	s_cmp_lg_u32 s9, 0
	s_cbranch_scc0 .Lagqa_noresc_7
	s_nop 15
	v_sub_f32_e32 v218, v218, v170
	v_sub_f32_e32 v219, v219, v170
	v_sub_f32_e32 v220, v220, v170
	v_sub_f32_e32 v221, v221, v170
	v_sub_f32_e32 v222, v222, v170
	v_sub_f32_e32 v223, v223, v170
	v_sub_f32_e32 v224, v224, v170
	v_sub_f32_e32 v225, v225, v170
	v_sub_f32_e32 v226, v226, v170
	v_sub_f32_e32 v227, v227, v170
	v_sub_f32_e32 v228, v228, v170
	v_sub_f32_e32 v229, v229, v170
	v_sub_f32_e32 v230, v230, v170
	v_sub_f32_e32 v231, v231, v170
	v_sub_f32_e32 v232, v232, v170
	v_sub_f32_e32 v233, v233, v170
	v_sub_f32_e32 v32, v32, v170
	v_sub_f32_e32 v33, v33, v170
	v_sub_f32_e32 v34, v34, v170
	v_sub_f32_e32 v35, v35, v170
	v_sub_f32_e32 v36, v36, v170
	v_sub_f32_e32 v37, v37, v170
	v_sub_f32_e32 v38, v38, v170
	v_sub_f32_e32 v39, v39, v170
	v_sub_f32_e32 v40, v40, v170
	v_sub_f32_e32 v41, v41, v170
	v_sub_f32_e32 v42, v42, v170
	v_sub_f32_e32 v43, v43, v170
	v_sub_f32_e32 v44, v44, v170
	v_sub_f32_e32 v45, v45, v170
	v_sub_f32_e32 v46, v46, v170
	v_sub_f32_e32 v47, v47, v170
	v_sub_f32_e32 v48, v48, v170
	v_sub_f32_e32 v49, v49, v170
	v_sub_f32_e32 v50, v50, v170
	v_sub_f32_e32 v51, v51, v170
	v_sub_f32_e32 v52, v52, v170
	v_sub_f32_e32 v53, v53, v170
	v_sub_f32_e32 v54, v54, v170
	v_sub_f32_e32 v55, v55, v170
	v_sub_f32_e32 v56, v56, v170
	v_sub_f32_e32 v57, v57, v170
	v_sub_f32_e32 v58, v58, v170
	v_sub_f32_e32 v59, v59, v170
	v_sub_f32_e32 v60, v60, v170
	v_sub_f32_e32 v61, v61, v170
	v_sub_f32_e32 v62, v62, v170
	v_sub_f32_e32 v63, v63, v170
	v_mul_f32_e32 v0, v0, v166
	v_mul_f32_e32 v1, v1, v166
	v_mul_f32_e32 v2, v2, v166
	v_mul_f32_e32 v3, v3, v166
	v_mul_f32_e32 v4, v4, v166
	v_mul_f32_e32 v5, v5, v166
	v_mul_f32_e32 v6, v6, v166
	v_mul_f32_e32 v7, v7, v166
	v_mul_f32_e32 v8, v8, v166
	v_mul_f32_e32 v9, v9, v166
	v_mul_f32_e32 v10, v10, v166
	v_mul_f32_e32 v11, v11, v166
	v_mul_f32_e32 v12, v12, v166
	v_mul_f32_e32 v13, v13, v166
	v_mul_f32_e32 v14, v14, v166
	v_mul_f32_e32 v15, v15, v166
	v_mul_f32_e32 v16, v16, v166
	v_mul_f32_e32 v17, v17, v166
	v_mul_f32_e32 v18, v18, v166
	v_mul_f32_e32 v19, v19, v166
	v_mul_f32_e32 v20, v20, v166
	v_mul_f32_e32 v21, v21, v166
	v_mul_f32_e32 v22, v22, v166
	v_mul_f32_e32 v23, v23, v166
	v_mul_f32_e32 v24, v24, v166
	v_mul_f32_e32 v25, v25, v166
	v_mul_f32_e32 v26, v26, v166
	v_mul_f32_e32 v27, v27, v166
	v_mul_f32_e32 v28, v28, v166
	v_mul_f32_e32 v29, v29, v166
	v_mul_f32_e32 v30, v30, v166
	v_mul_f32_e32 v31, v31, v166
	v_add_u32_e32 v170, 64, v175
	ds_bpermute_b32 v173, v170, v166
	v_mul_f32_e32 v234, v234, v166
	s_waitcnt lgkmcnt(0)
	v_mul_f32_e32 v235, v235, v173
.Lagqa_noresc_7:
	s_waitcnt lgkmcnt(8)
	s_barrier
	ds_read_b128 v[136:139], v243 offset:9216
	ds_read_b128 v[140:143], v243 offset:13824
	ds_read_b128 v[144:147], v243 offset:9248
	ds_read_b128 v[148:151], v243 offset:13856
	s_waitcnt lgkmcnt(10)
	v_mfma_f32_32x32x16_bf16 v[0:15], v[176:179], v[96:99], v[0:15]
	v_max3_f32 v168, v32, v33, v34
	v_max3_f32 v170, v48, v49, v50
	v_max3_f32 v168, v168, v35, v36
	v_max3_f32 v170, v170, v51, v52
	v_max3_f32 v168, v168, v37, v38
	s_mov_b32 s55, s52
	s_mov_b32 s52, s53
	s_mov_b32 s53, s54
	s_mov_b32 s54, s55
	s_mov_b32 s9, 0
	s_waitcnt lgkmcnt(8)
	v_mfma_f32_32x32x16_bf16 v[16:31], v[180:183], v[96:99], v[16:31]
	v_max3_f32 v170, v170, v53, v54
	v_max3_f32 v168, v168, v39, v40
	v_max3_f32 v170, v170, v55, v56
	v_max3_f32 v168, v168, v41, v42
	v_max3_f32 v170, v170, v57, v58
	v_add_u32_e32 v163, s53, v240
	v_add_u32_e32 v164, s54, v241
	v_mfma_f32_16x16x32_bf16 v[234:237], v[246:249], v[96:99], v[234:237]
	v_max3_f32 v168, v168, v43, v44
	v_max3_f32 v170, v170, v59, v60
	v_max3_f32 v168, v168, v45, v46
	v_max3_f32 v170, v170, v61, v62
	v_max3_f32 v168, v168, v170, v47
	s_waitcnt lgkmcnt(3)
	v_mfma_f32_32x32x16_bf16 v[64:79], v[136:139], v[112:115], v[218:233]
	v_max_f32_e32 v168, v168, v63
	v_cmp_lt_f32_e32 vcc, 0x41000000, v168
	s_cbranch_vccz .Lagqa_nors_8
	v_mov_b32_e32 v170, v168
	s_nop 1
	v_permlane32_swap_b32_e32 v168, v170
	v_max_f32_e32 v168, v168, v170
	v_max_f32_e32 v170, 0, v168
	v_exp_f32_e64 v166, -v170
	v_sub_f32_e32 v32, v32, v170
	v_sub_f32_e32 v33, v33, v170
	v_sub_f32_e32 v34, v34, v170
	v_sub_f32_e32 v35, v35, v170
	v_sub_f32_e32 v36, v36, v170
	v_sub_f32_e32 v37, v37, v170
	v_sub_f32_e32 v38, v38, v170
	v_sub_f32_e32 v39, v39, v170
	v_sub_f32_e32 v40, v40, v170
	v_sub_f32_e32 v41, v41, v170
	v_sub_f32_e32 v42, v42, v170
	v_sub_f32_e32 v43, v43, v170
	v_sub_f32_e32 v44, v44, v170
	v_sub_f32_e32 v45, v45, v170
	v_sub_f32_e32 v46, v46, v170
	v_sub_f32_e32 v47, v47, v170
	v_sub_f32_e32 v48, v48, v170
	v_sub_f32_e32 v49, v49, v170
	v_sub_f32_e32 v50, v50, v170
	v_sub_f32_e32 v51, v51, v170
	v_sub_f32_e32 v52, v52, v170
	v_sub_f32_e32 v53, v53, v170
	v_sub_f32_e32 v54, v54, v170
	v_sub_f32_e32 v55, v55, v170
	v_sub_f32_e32 v56, v56, v170
	v_sub_f32_e32 v57, v57, v170
	v_sub_f32_e32 v58, v58, v170
	v_sub_f32_e32 v59, v59, v170
	v_sub_f32_e32 v60, v60, v170
	v_sub_f32_e32 v61, v61, v170
	v_sub_f32_e32 v62, v62, v170
	v_sub_f32_e32 v63, v63, v170
	s_mov_b32 s9, 1
.Lagqa_nors_8:
	v_exp_f32_e32 v32, v32
	ds_read_b128 v[136:139], v243 offset:9280
	ds_read_b64_tr_b16 v[192:193], v162 offset:3072
	ds_read_b64_tr_b16 v[194:195], v162 offset:4608
	v_mfma_f32_32x32x16_bf16 v[0:15], v[184:187], v[104:107], v[0:15]
	v_exp_f32_e32 v48, v48
	v_exp_f32_e32 v33, v33
	v_exp_f32_e32 v49, v49
	ds_read_b64_tr_b16 v[196:197], v162 offset:3136
	ds_read_b64_tr_b16 v[198:199], v162 offset:4672
	s_waitcnt lgkmcnt(7)
	v_mfma_f32_32x32x16_bf16 v[80:95], v[140:143], v[112:115], v[218:233]
	v_exp_f32_e32 v34, v34
	v_exp_f32_e32 v50, v50
	ds_read_b128 v[140:143], v243 offset:13888
	ds_read_b64_tr_b16 v[200:201], v162 offset:9216
	ds_read_b64_tr_b16 v[202:203], v162 offset:10752
	v_mfma_f32_32x32x16_bf16 v[16:31], v[188:191], v[104:107], v[16:31]
	v_cvt_pk_bf16_f32 v96, v32, v33
	v_exp_f32_e32 v35, v35
	v_exp_f32_e32 v51, v51
	ds_read_b64_tr_b16 v[204:205], v162 offset:9280
	ds_read_b64_tr_b16 v[206:207], v162 offset:10816
	s_waitcnt lgkmcnt(11)
	v_mfma_f32_32x32x16_bf16 v[64:79], v[144:147], v[116:119], v[64:79]
	v_exp_f32_e32 v36, v36
	v_exp_f32_e32 v52, v52
	v_cvt_pk_bf16_f32 v97, v34, v35
	ds_read_b128 v[144:147], v243 offset:9312
	v_mfma_f32_16x16x32_bf16 v[234:237], v[246:249], v[104:107], v[234:237]
	v_cvt_pk_bf16_f32 v104, v48, v49
	v_cvt_pk_bf16_f32 v105, v50, v51
	v_exp_f32_e32 v37, v37
	v_exp_f32_e32 v53, v53
	s_waitcnt lgkmcnt(11)
	v_mfma_f32_32x32x16_bf16 v[80:95], v[148:151], v[116:119], v[80:95]
	v_exp_f32_e32 v38, v38
	v_exp_f32_e32 v54, v54
	v_cvt_pk_bf16_f32 v98, v36, v37
	ds_read_b128 v[148:151], v243 offset:13920
	s_waitcnt lgkmcnt(9)
	v_mfma_f32_32x32x16_bf16 v[0:15], v[192:195], v[100:103], v[0:15]
	v_cvt_pk_bf16_f32 v106, v52, v53
	v_exp_f32_e32 v39, v39
	v_exp_f32_e32 v55, v55
	v_mfma_f32_32x32x16_bf16 v[64:79], v[136:139], v[120:123], v[64:79]
	v_exp_f32_e32 v40, v40
	v_exp_f32_e32 v56, v56
	s_waitcnt vmcnt(0)
	ds_write_b128 v164, v[156:159]
	s_waitcnt lgkmcnt(8)
	v_mfma_f32_32x32x16_bf16 v[16:31], v[196:199], v[100:103], v[16:31]
	v_cvt_pk_bf16_f32 v99, v38, v39
	v_cvt_pk_bf16_f32 v107, v54, v55
	v_exp_f32_e32 v41, v41
	v_exp_f32_e32 v57, v57
	s_waitcnt lgkmcnt(7)
	v_mfma_f32_32x32x16_bf16 v[80:95], v[140:143], v[120:123], v[80:95]
	v_exp_f32_e32 v42, v42
	v_exp_f32_e32 v58, v58
	v_mfma_f32_16x16x32_bf16 v[234:237], v[246:249], v[100:103], v[234:237]
	v_cvt_pk_bf16_f32 v100, v40, v41
	v_exp_f32_e32 v43, v43
	v_exp_f32_e32 v59, v59
	ds_read_b64_tr_b16 v[176:177], v163 offset:0
	ds_read_b64_tr_b16 v[178:179], v163 offset:1536
	s_waitcnt lgkmcnt(4)
	v_mfma_f32_32x32x16_bf16 v[64:79], v[144:147], v[124:127], v[64:79]
	v_exp_f32_e32 v44, v44
	v_exp_f32_e32 v60, v60
	v_cvt_pk_bf16_f32 v101, v42, v43
	ds_read_b64_tr_b16 v[180:181], v163 offset:64
	ds_read_b64_tr_b16 v[182:183], v163 offset:1600
	v_mfma_f32_32x32x16_bf16 v[0:15], v[200:203], v[108:111], v[0:15]
	v_exp_f32_e32 v45, v45
	v_exp_f32_e32 v61, v61
	v_exp_f32_e32 v46, v46
	ds_read_b64_tr_b16 v[184:185], v163 offset:6144
	ds_read_b64_tr_b16 v[186:187], v163 offset:7680
	s_waitcnt lgkmcnt(7)
	v_mfma_f32_32x32x16_bf16 v[80:95], v[148:151], v[124:127], v[80:95]
	v_exp_f32_e32 v62, v62
	v_cvt_pk_bf16_f32 v102, v44, v45
	v_exp_f32_e32 v47, v47
	ds_read_b64_tr_b16 v[188:189], v163 offset:6208
	ds_read_b64_tr_b16 v[190:191], v163 offset:7744
	v_mfma_f32_32x32x16_bf16 v[16:31], v[204:207], v[108:111], v[16:31]
	v_exp_f32_e32 v63, v63
	v_cvt_pk_bf16_f32 v103, v46, v47
	v_mfma_f32_16x16x32_bf16 v[234:237], v[246:249], v[108:111], v[234:237]
	v_cvt_pk_bf16_f32 v108, v56, v57
	v_cvt_pk_bf16_f32 v109, v58, v59
	v_cvt_pk_bf16_f32 v110, v60, v61
	v_cvt_pk_bf16_f32 v111, v62, v63
	s_cmp_lg_u32 s9, 0
	s_cbranch_scc0 .Lagqa_noresc_9
	s_nop 15
	v_sub_f32_e32 v218, v218, v170
	v_sub_f32_e32 v219, v219, v170
	v_sub_f32_e32 v220, v220, v170
	v_sub_f32_e32 v221, v221, v170
	v_sub_f32_e32 v222, v222, v170
	v_sub_f32_e32 v223, v223, v170
	v_sub_f32_e32 v224, v224, v170
	v_sub_f32_e32 v225, v225, v170
	v_sub_f32_e32 v226, v226, v170
	v_sub_f32_e32 v227, v227, v170
	v_sub_f32_e32 v228, v228, v170
	v_sub_f32_e32 v229, v229, v170
	v_sub_f32_e32 v230, v230, v170
	v_sub_f32_e32 v231, v231, v170
	v_sub_f32_e32 v232, v232, v170
	v_sub_f32_e32 v233, v233, v170
	v_sub_f32_e32 v64, v64, v170
	v_sub_f32_e32 v65, v65, v170
	v_sub_f32_e32 v66, v66, v170
	v_sub_f32_e32 v67, v67, v170
	v_sub_f32_e32 v68, v68, v170
	v_sub_f32_e32 v69, v69, v170
	v_sub_f32_e32 v70, v70, v170
	v_sub_f32_e32 v71, v71, v170
	v_sub_f32_e32 v72, v72, v170
	v_sub_f32_e32 v73, v73, v170
	v_sub_f32_e32 v74, v74, v170
	v_sub_f32_e32 v75, v75, v170
	v_sub_f32_e32 v76, v76, v170
	v_sub_f32_e32 v77, v77, v170
	v_sub_f32_e32 v78, v78, v170
	v_sub_f32_e32 v79, v79, v170
	v_sub_f32_e32 v80, v80, v170
	v_sub_f32_e32 v81, v81, v170
	v_sub_f32_e32 v82, v82, v170
	v_sub_f32_e32 v83, v83, v170
	v_sub_f32_e32 v84, v84, v170
	v_sub_f32_e32 v85, v85, v170
	v_sub_f32_e32 v86, v86, v170
	v_sub_f32_e32 v87, v87, v170
	v_sub_f32_e32 v88, v88, v170
	v_sub_f32_e32 v89, v89, v170
	v_sub_f32_e32 v90, v90, v170
	v_sub_f32_e32 v91, v91, v170
	v_sub_f32_e32 v92, v92, v170
	v_sub_f32_e32 v93, v93, v170
	v_sub_f32_e32 v94, v94, v170
	v_sub_f32_e32 v95, v95, v170
	v_mul_f32_e32 v0, v0, v166
	v_mul_f32_e32 v1, v1, v166
	v_mul_f32_e32 v2, v2, v166
	v_mul_f32_e32 v3, v3, v166
	v_mul_f32_e32 v4, v4, v166
	v_mul_f32_e32 v5, v5, v166
	v_mul_f32_e32 v6, v6, v166
	v_mul_f32_e32 v7, v7, v166
	v_mul_f32_e32 v8, v8, v166
	v_mul_f32_e32 v9, v9, v166
	v_mul_f32_e32 v10, v10, v166
	v_mul_f32_e32 v11, v11, v166
	v_mul_f32_e32 v12, v12, v166
	v_mul_f32_e32 v13, v13, v166
	v_mul_f32_e32 v14, v14, v166
	v_mul_f32_e32 v15, v15, v166
	v_mul_f32_e32 v16, v16, v166
	v_mul_f32_e32 v17, v17, v166
	v_mul_f32_e32 v18, v18, v166
	v_mul_f32_e32 v19, v19, v166
	v_mul_f32_e32 v20, v20, v166
	v_mul_f32_e32 v21, v21, v166
	v_mul_f32_e32 v22, v22, v166
	v_mul_f32_e32 v23, v23, v166
	v_mul_f32_e32 v24, v24, v166
	v_mul_f32_e32 v25, v25, v166
	v_mul_f32_e32 v26, v26, v166
	v_mul_f32_e32 v27, v27, v166
	v_mul_f32_e32 v28, v28, v166
	v_mul_f32_e32 v29, v29, v166
	v_mul_f32_e32 v30, v30, v166
	v_mul_f32_e32 v31, v31, v166
	v_add_u32_e32 v170, 64, v175
	ds_bpermute_b32 v173, v170, v166
	v_mul_f32_e32 v234, v234, v166
	s_waitcnt lgkmcnt(0)
	v_mul_f32_e32 v235, v235, v173
